# hand-written EpiVt epilogue (gelu + bf16 stores + LN partial sums) on top of EpiConv rewrite, conditional wbl2 in local mode
# speedup vs baseline: 1.0410x; 1.0152x over previous
; #define PG8_STAGE(bufoff, gbase, voff) do { _Pragma("unroll") for (int _i = 0; _i < 2; ++_i) \
;         __builtin_amdgcn_global_load_lds((const __attribute__((address_space(1))) unsigned*)((const char*)(gbase) + (voff)[_i]), (LAS unsigned*)(lds + (bufoff) + ldsw + _i * 8192), 16, 0, 0); } while (0)
; #define PG8_LDA(dst, b, h) do { _Pragma("unroll") for (int m = 0; m < 4; ++m) _Pragma("unroll") for (int k = 0; k < 2; ++k) dst[m][k] = *(const LAS bf16x8*)(lds + PG8_SA(b, h) + aoff + m * 2048 + k * 1024); } while (0)
; #define PG8_LDB(dst, b, h) do { _Pragma("unroll") for (int n = 0; n < 2; ++n) _Pragma("unroll") for (int k = 0; k < 2; ++k) dst[n][k] = *(const LAS bf16x8*)(lds + PG8_SB(b, h) + boff + n * 2048 + k * 1024); } while (0)
; #define PG8_WAIT_V(n) asm volatile("s_waitcnt vmcnt(" #n ")" ::: "memory")
; #define PG8_WAIT_L(n) asm volatile("s_waitcnt lgkmcnt(" #n ")" ::: "memory")
; #define PG8_BAR __builtin_amdgcn_s_barrier()
; #define PG8_SCHED __builtin_amdgcn_sched_barrier(0)
; template <class Epi>
; __device__ __forceinline__ void gemm_phase(LAS unsigned char* lds, const Gemm g, const StaticOrder& S_in, const Epi& E, int sw) {
;     ...
;         for (int t = 0; t < nt; t += 2) {
;             const bool last = (t == nt - 2);
;             const char* a1 = cA + (size_t)(t + 1) * kstep;
;             const char* a2 = last ? nA : cA + (size_t)(t + 2) * kstep; const char* b2 = last ? nB : cB + (size_t)(t + 2) * kstep;
;             const char* a3 = a2 + kstep; const char* b3 = b2 + kstep;
;             PG8_LDB(B0, 0, 0); PG8_SCHED; PG8_LDA(At, 0, 0); PG8_STAGE(PG8_SA(1, 1), a1 + hstepA, voffA);
;             PG8_WAIT_L(8); PG8_BAR; PG8_WAIT_L(0); PG8_MMA(0, 0, At, B0); PG8_BAR; PG8_SCHED;
;             PG8_LDB(B1, 0, 1); PG8_STAGE(PG8_SB(0, 0), b2, voffB);
;             PG8_BAR; PG8_WAIT_L(0); PG8_MMA(0, 1, At, B1); PG8_BAR;
;             PG8_LDA(At, 0, 1); PG8_STAGE(PG8_SA(0, 0), a2, voffA);
;             PG8_BAR; PG8_WAIT_L(0); PG8_MMA(1, 0, At, B0); PG8_BAR; PG8_SCHED;
;             PG8_STAGE(PG8_SB(0, 1), b2 + hstepB, voffB);
;             PG8_WAIT_V(6); PG8_BAR; PG8_MMA(1, 1, At, B1); PG8_BAR;
;             PG8_LDB(B0, 1, 0); PG8_SCHED; PG8_LDA(At, 1, 0); PG8_STAGE(PG8_SA(0, 1), a2 + hstepA, voffA);
;             PG8_WAIT_L(8); PG8_BAR; PG8_WAIT_L(0); PG8_MMA(0, 0, At, B0); PG8_BAR; PG8_SCHED;
.LBB0_771:
	s_add_u32 s20, s0, 0xfffc0080
	s_addc_u32 s21, s1, -1
	s_add_i32 s51, 0, 0x10000
	v_add_u32_e32 v0, s51, v171
	ds_read_b128 v[142:145], v0
	ds_read_b128 v[146:149], v0 offset:1024
	ds_read_b128 v[150:153], v0 offset:2048
	ds_read_b128 v[154:157], v0 offset:3072
	s_cmp_eq_u32 s50, 12
	s_cselect_b32 s23, s9, s21
	s_cselect_b32 s22, s17, s20
	s_cselect_b32 s21, s7, s49
	s_cselect_b32 s20, s19, s48
	v_lshl_add_u64 v[192:193], s[0:1], 0, v[138:139]
	s_add_i32 m0, s34, 0xc000
	ds_read_b128 v[158:161], v232
	ds_read_b128 v[162:165], v232 offset:1024
	ds_read_b128 v[166:169], v232 offset:2048
	ds_read_b128 v[172:175], v232 offset:3072
	ds_read_b128 v[176:179], v232 offset:4096
	ds_read_b128 v[180:183], v232 offset:5120
	ds_read_b128 v[184:187], v232 offset:6144
	ds_read_b128 v[188:191], v232 offset:7168
	global_load_lds_dwordx4 v[192:193], off
	v_lshl_add_u64 v[192:193], s[0:1], 0, v[140:141]
	s_add_i32 m0, s34, 0xe000
	s_nop 0
	global_load_lds_dwordx4 v[192:193], off
	s_waitcnt lgkmcnt(8)
	s_barrier
	s_waitcnt lgkmcnt(0)
	s_setprio 1
	s_waitcnt lgkmcnt(0)
	v_mfma_f32_16x16x32_bf16 v[126:129], v[142:145], v[158:161], v[126:129]
	v_mfma_f32_16x16x32_bf16 v[122:125], v[150:153], v[158:161], v[122:125]
	v_mfma_f32_16x16x32_bf16 v[118:121], v[142:145], v[166:169], v[118:121]
	v_mfma_f32_16x16x32_bf16 v[114:117], v[150:153], v[166:169], v[114:117]
	v_mfma_f32_16x16x32_bf16 v[90:93], v[142:145], v[176:179], v[90:93]
	v_mfma_f32_16x16x32_bf16 v[110:113], v[150:153], v[176:179], v[110:113]
	v_mfma_f32_16x16x32_bf16 v[86:89], v[142:145], v[184:187], v[86:89]
	v_mfma_f32_16x16x32_bf16 v[106:109], v[150:153], v[184:187], v[106:109]
	v_mfma_f32_16x16x32_bf16 v[126:129], v[146:149], v[162:165], v[126:129]
	v_mfma_f32_16x16x32_bf16 v[122:125], v[154:157], v[162:165], v[122:125]
	v_mfma_f32_16x16x32_bf16 v[118:121], v[146:149], v[172:175], v[118:121]
	v_mfma_f32_16x16x32_bf16 v[114:117], v[154:157], v[172:175], v[114:117]
	v_mfma_f32_16x16x32_bf16 v[90:93], v[146:149], v[180:183], v[90:93]
	v_mfma_f32_16x16x32_bf16 v[110:113], v[154:157], v[180:183], v[110:113]
	v_mfma_f32_16x16x32_bf16 v[86:89], v[146:149], v[188:191], v[86:89]
	v_mfma_f32_16x16x32_bf16 v[106:109], v[154:157], v[188:191], v[106:109]
	s_setprio 0
	s_barrier
	s_add_i32 s54, 0, 0x14000
	s_add_i32 s51, s51, s29
	v_add_u32_e32 v0, s54, v171
	v_lshl_add_u64 v[208:209], s[20:21], 0, v[132:133]
	s_mov_b32 m0, s51
	ds_read_b128 v[192:195], v0
	ds_read_b128 v[196:199], v0 offset:1024
	ds_read_b128 v[200:203], v0 offset:2048
	ds_read_b128 v[204:207], v0 offset:3072
	global_load_lds_dwordx4 v[208:209], off
	v_lshl_add_u64 v[210:211], s[20:21], 0, v[136:137]
	s_add_i32 m0, s51, 0x2000
	s_nop 0
	global_load_lds_dwordx4 v[210:211], off
	s_barrier
	s_waitcnt lgkmcnt(0)
	s_setprio 1
	s_waitcnt lgkmcnt(0)
	v_mfma_f32_16x16x32_bf16 v[62:65], v[192:195], v[158:161], v[62:65]
	v_mfma_f32_16x16x32_bf16 v[58:61], v[200:203], v[158:161], v[58:61]
	v_mfma_f32_16x16x32_bf16 v[54:57], v[192:195], v[166:169], v[54:57]
	v_mfma_f32_16x16x32_bf16 v[50:53], v[200:203], v[166:169], v[50:53]
	v_mfma_f32_16x16x32_bf16 v[26:29], v[192:195], v[176:179], v[26:29]
	v_mfma_f32_16x16x32_bf16 v[46:49], v[200:203], v[176:179], v[46:49]
	v_mfma_f32_16x16x32_bf16 v[22:25], v[192:195], v[184:187], v[22:25]
	v_mfma_f32_16x16x32_bf16 v[42:45], v[200:203], v[184:187], v[42:45]
	v_mfma_f32_16x16x32_bf16 v[62:65], v[196:199], v[162:165], v[62:65]
	v_mfma_f32_16x16x32_bf16 v[58:61], v[204:207], v[162:165], v[58:61]
	v_mfma_f32_16x16x32_bf16 v[54:57], v[196:199], v[172:175], v[54:57]
	v_mfma_f32_16x16x32_bf16 v[50:53], v[204:207], v[172:175], v[50:53]
	v_mfma_f32_16x16x32_bf16 v[26:29], v[196:199], v[180:183], v[26:29]
	v_mfma_f32_16x16x32_bf16 v[46:49], v[204:207], v[180:183], v[46:49]
	v_mfma_f32_16x16x32_bf16 v[22:25], v[196:199], v[188:191], v[22:25]
	v_mfma_f32_16x16x32_bf16 v[42:45], v[204:207], v[188:191], v[42:45]
	s_setprio 0
	s_mov_b32 m0, s34
	v_lshl_add_u64 v[212:213], s[22:23], 0, v[130:131]
	s_barrier
	ds_read_b128 v[158:161], v232 offset:16384
	ds_read_b128 v[162:165], v232 offset:17408
	ds_read_b128 v[166:169], v232 offset:18432
	ds_read_b128 v[172:175], v232 offset:19456
	ds_read_b128 v[176:179], v232 offset:20480
	ds_read_b128 v[180:183], v232 offset:21504
	ds_read_b128 v[184:187], v232 offset:22528
	ds_read_b128 v[188:191], v232 offset:23552
	global_load_lds_dwordx4 v[212:213], off
	v_lshl_add_u64 v[214:215], s[22:23], 0, v[134:135]
	s_mov_b32 m0, s35
	s_nop 0
	global_load_lds_dwordx4 v[214:215], off
	s_barrier
	s_waitcnt lgkmcnt(0)
	s_setprio 1
	s_waitcnt lgkmcnt(0)
	v_mfma_f32_16x16x32_bf16 v[78:81], v[142:145], v[158:161], v[78:81]
	v_mfma_f32_16x16x32_bf16 v[102:105], v[150:153], v[158:161], v[102:105]
	v_mfma_f32_16x16x32_bf16 v[74:77], v[142:145], v[166:169], v[74:77]
	v_mfma_f32_16x16x32_bf16 v[98:101], v[150:153], v[166:169], v[98:101]
	v_mfma_f32_16x16x32_bf16 v[70:73], v[142:145], v[176:179], v[70:73]
	v_mfma_f32_16x16x32_bf16 v[94:97], v[150:153], v[176:179], v[94:97]
	v_mfma_f32_16x16x32_bf16 v[66:69], v[142:145], v[184:187], v[66:69]
	v_mfma_f32_16x16x32_bf16 v[82:85], v[150:153], v[184:187], v[82:85]
	v_mfma_f32_16x16x32_bf16 v[78:81], v[146:149], v[162:165], v[78:81]
	v_mfma_f32_16x16x32_bf16 v[102:105], v[154:157], v[162:165], v[102:105]
	v_mfma_f32_16x16x32_bf16 v[74:77], v[146:149], v[172:175], v[74:77]
	v_mfma_f32_16x16x32_bf16 v[98:101], v[154:157], v[172:175], v[98:101]
	v_mfma_f32_16x16x32_bf16 v[70:73], v[146:149], v[180:183], v[70:73]
	v_mfma_f32_16x16x32_bf16 v[94:97], v[154:157], v[180:183], v[94:97]
	v_mfma_f32_16x16x32_bf16 v[66:69], v[146:149], v[188:191], v[66:69]
	v_mfma_f32_16x16x32_bf16 v[82:85], v[154:157], v[188:191], v[82:85]
	s_setprio 0
	s_barrier
; #define PG8_STAGE(bufoff, gbase, voff) do { _Pragma("unroll") for (int _i = 0; _i < 2; ++_i) \
;         __builtin_amdgcn_global_load_lds((const __attribute__((address_space(1))) unsigned*)((const char*)(gbase) + (voff)[_i]), (LAS unsigned*)(lds + (bufoff) + ldsw + _i * 8192), 16, 0, 0); } while (0)
; #define PG8_LDA(dst, b, h) do { _Pragma("unroll") for (int m = 0; m < 4; ++m) _Pragma("unroll") for (int k = 0; k < 2; ++k) dst[m][k] = *(const LAS bf16x8*)(lds + PG8_SA(b, h) + aoff + m * 2048 + k * 1024); } while (0)
; #define PG8_LDB(dst, b, h) do { _Pragma("unroll") for (int n = 0; n < 2; ++n) _Pragma("unroll") for (int k = 0; k < 2; ++k) dst[n][k] = *(const LAS bf16x8*)(lds + PG8_SB(b, h) + boff + n * 2048 + k * 1024); } while (0)
; #define PG8_MMA(ai, bj, At, Bt) do { __builtin_amdgcn_s_setprio(1); _Pragma("unroll") for (int m = 0; m < 4; ++m) _Pragma("unroll") for (int n = 0; n < 2; ++n) _Pragma("unroll") for (int k = 0; k < 2; ++k) \
;         acc[ai][bj][m][n] = __builtin_amdgcn_mfma_f32_16x16x32_bf16(Bt[n][k], At[m][k], acc[ai][bj][m][n], 0, 0, 0); __builtin_amdgcn_s_setprio(0); } while (0)
; #define PG8_WAIT_V(n) asm volatile("s_waitcnt vmcnt(" #n ")" ::: "memory")
; #define PG8_WAIT_L(n) asm volatile("s_waitcnt lgkmcnt(" #n ")" ::: "memory")
; #define PG8_BAR __builtin_amdgcn_s_barrier()
; #define PG8_SCHED __builtin_amdgcn_sched_barrier(0)
; template <class Epi>
; __device__ __forceinline__ void gemm_phase(LAS unsigned char* lds, const Gemm g, const StaticOrder& S_in, const Epi& E, int sw) {
;     ...
;             PG8_WAIT_V(6); PG8_BAR; PG8_MMA(1, 1, At, B1); PG8_BAR;
;             PG8_LDB(B0, 1, 0); PG8_SCHED; PG8_LDA(At, 1, 0); PG8_STAGE(PG8_SA(0, 1), a2 + hstepA, voffA);
;             PG8_WAIT_L(8); PG8_BAR; PG8_WAIT_L(0); PG8_MMA(0, 0, At, B0); PG8_BAR; PG8_SCHED;
;             PG8_LDB(B1, 1, 1); PG8_STAGE(PG8_SB(1, 0), b3, voffB);
;             PG8_BAR; PG8_WAIT_L(0); PG8_MMA(0, 1, At, B1); PG8_BAR;
;             PG8_LDA(At, 1, 1); PG8_STAGE(PG8_SA(1, 0), a3, voffA);
;             PG8_BAR; PG8_WAIT_L(0); PG8_MMA(1, 0, At, B0); PG8_BAR; PG8_SCHED;
	s_add_u32 s52, s20, 0x40000
	s_addc_u32 s53, s21, 0
	s_add_i32 s51, s54, s29
	v_lshl_add_u64 v[142:143], s[52:53], 0, v[132:133]
	s_mov_b32 m0, s51
	s_nop 0
	global_load_lds_dwordx4 v[142:143], off
	v_lshl_add_u64 v[142:143], s[52:53], 0, v[136:137]
	s_add_i32 m0, s51, 0x2000
	s_nop 0
	global_load_lds_dwordx4 v[142:143], off
	s_waitcnt vmcnt(6)
	s_barrier
	s_setprio 1
	v_mfma_f32_16x16x32_bf16 v[14:17], v[192:195], v[158:161], v[14:17]
	v_mfma_f32_16x16x32_bf16 v[38:41], v[200:203], v[158:161], v[38:41]
	v_mfma_f32_16x16x32_bf16 v[10:13], v[192:195], v[166:169], v[10:13]
	v_mfma_f32_16x16x32_bf16 v[34:37], v[200:203], v[166:169], v[34:37]
	v_mfma_f32_16x16x32_bf16 v[6:9], v[192:195], v[176:179], v[6:9]
	v_mfma_f32_16x16x32_bf16 v[30:33], v[200:203], v[176:179], v[30:33]
	v_mfma_f32_16x16x32_bf16 v[2:5], v[192:195], v[184:187], v[2:5]
	v_mfma_f32_16x16x32_bf16 v[18:21], v[200:203], v[184:187], v[18:21]
	v_mfma_f32_16x16x32_bf16 v[14:17], v[196:199], v[162:165], v[14:17]
	v_mfma_f32_16x16x32_bf16 v[38:41], v[204:207], v[162:165], v[38:41]
	v_mfma_f32_16x16x32_bf16 v[10:13], v[196:199], v[172:175], v[10:13]
	v_mfma_f32_16x16x32_bf16 v[34:37], v[204:207], v[172:175], v[34:37]
	v_mfma_f32_16x16x32_bf16 v[6:9], v[196:199], v[180:183], v[6:9]
	v_mfma_f32_16x16x32_bf16 v[30:33], v[204:207], v[180:183], v[30:33]
	v_mfma_f32_16x16x32_bf16 v[2:5], v[196:199], v[188:191], v[2:5]
	v_mfma_f32_16x16x32_bf16 v[18:21], v[204:207], v[188:191], v[18:21]
	s_setprio 0
	s_add_i32 s51, 0, 0x18000
	v_add_u32_e32 v0, s51, v171
	s_barrier
	ds_read_b128 v[142:145], v0
	ds_read_b128 v[146:149], v0 offset:1024
	ds_read_b128 v[150:153], v0 offset:2048
	ds_read_b128 v[154:157], v0 offset:3072
	s_add_u32 s22, s22, 0x40000
	s_addc_u32 s23, s23, 0
	s_mov_b32 m0, s36
	v_lshl_add_u64 v[192:193], s[22:23], 0, v[130:131]
	ds_read_b128 v[158:161], v232 offset:32768
	ds_read_b128 v[162:165], v232 offset:33792
	ds_read_b128 v[166:169], v232 offset:34816
	ds_read_b128 v[172:175], v232 offset:35840
	ds_read_b128 v[176:179], v232 offset:36864
	ds_read_b128 v[180:183], v232 offset:37888
	ds_read_b128 v[184:187], v232 offset:38912
	ds_read_b128 v[188:191], v232 offset:39936
	global_load_lds_dwordx4 v[192:193], off
	v_lshl_add_u64 v[192:193], s[22:23], 0, v[134:135]
	s_mov_b32 m0, s37
	s_nop 0
	global_load_lds_dwordx4 v[192:193], off
	s_waitcnt lgkmcnt(8)
	s_barrier
	s_waitcnt lgkmcnt(0)
	s_setprio 1
	s_waitcnt lgkmcnt(0)
	v_mfma_f32_16x16x32_bf16 v[126:129], v[142:145], v[158:161], v[126:129]
	v_mfma_f32_16x16x32_bf16 v[122:125], v[150:153], v[158:161], v[122:125]
	v_mfma_f32_16x16x32_bf16 v[118:121], v[142:145], v[166:169], v[118:121]
	v_mfma_f32_16x16x32_bf16 v[114:117], v[150:153], v[166:169], v[114:117]
	v_mfma_f32_16x16x32_bf16 v[90:93], v[142:145], v[176:179], v[90:93]
	v_mfma_f32_16x16x32_bf16 v[110:113], v[150:153], v[176:179], v[110:113]
	v_mfma_f32_16x16x32_bf16 v[86:89], v[142:145], v[184:187], v[86:89]
	v_mfma_f32_16x16x32_bf16 v[106:109], v[150:153], v[184:187], v[106:109]
	v_mfma_f32_16x16x32_bf16 v[126:129], v[146:149], v[162:165], v[126:129]
	v_mfma_f32_16x16x32_bf16 v[122:125], v[154:157], v[162:165], v[122:125]
	v_mfma_f32_16x16x32_bf16 v[118:121], v[146:149], v[172:175], v[118:121]
	v_mfma_f32_16x16x32_bf16 v[114:117], v[154:157], v[172:175], v[114:117]
	v_mfma_f32_16x16x32_bf16 v[90:93], v[146:149], v[180:183], v[90:93]
	v_mfma_f32_16x16x32_bf16 v[110:113], v[154:157], v[180:183], v[110:113]
	v_mfma_f32_16x16x32_bf16 v[86:89], v[146:149], v[188:191], v[86:89]
	v_mfma_f32_16x16x32_bf16 v[106:109], v[154:157], v[188:191], v[106:109]
	s_setprio 0
	s_barrier
	s_add_i32 s22, 0, 0x1c000
	s_add_i32 s23, s51, s29
	v_add_u32_e32 v0, s22, v171
	v_lshl_add_u64 v[208:209], v[208:209], 0, s[86:87]
	s_mov_b32 m0, s23
	ds_read_b128 v[192:195], v0
	ds_read_b128 v[196:199], v0 offset:1024
	ds_read_b128 v[200:203], v0 offset:2048
	ds_read_b128 v[204:207], v0 offset:3072
	global_load_lds_dwordx4 v[208:209], off
	v_lshl_add_u64 v[208:209], v[210:211], 0, s[86:87]
	s_add_i32 m0, s23, 0x2000
	s_nop 0
	global_load_lds_dwordx4 v[208:209], off
	s_barrier
	s_waitcnt lgkmcnt(0)
	s_setprio 1
	s_waitcnt lgkmcnt(0)
	v_mfma_f32_16x16x32_bf16 v[62:65], v[192:195], v[158:161], v[62:65]
	v_mfma_f32_16x16x32_bf16 v[58:61], v[200:203], v[158:161], v[58:61]
	v_mfma_f32_16x16x32_bf16 v[54:57], v[192:195], v[166:169], v[54:57]
	v_mfma_f32_16x16x32_bf16 v[50:53], v[200:203], v[166:169], v[50:53]
	v_mfma_f32_16x16x32_bf16 v[26:29], v[192:195], v[176:179], v[26:29]
	v_mfma_f32_16x16x32_bf16 v[46:49], v[200:203], v[176:179], v[46:49]
	v_mfma_f32_16x16x32_bf16 v[22:25], v[192:195], v[184:187], v[22:25]
	v_mfma_f32_16x16x32_bf16 v[42:45], v[200:203], v[184:187], v[42:45]
	v_mfma_f32_16x16x32_bf16 v[62:65], v[196:199], v[162:165], v[62:65]
	v_mfma_f32_16x16x32_bf16 v[58:61], v[204:207], v[162:165], v[58:61]
	v_mfma_f32_16x16x32_bf16 v[54:57], v[196:199], v[172:175], v[54:57]
	v_mfma_f32_16x16x32_bf16 v[50:53], v[204:207], v[172:175], v[50:53]
	v_mfma_f32_16x16x32_bf16 v[26:29], v[196:199], v[180:183], v[26:29]
	v_mfma_f32_16x16x32_bf16 v[46:49], v[204:207], v[180:183], v[46:49]
	v_mfma_f32_16x16x32_bf16 v[22:25], v[196:199], v[188:191], v[22:25]
	v_mfma_f32_16x16x32_bf16 v[42:45], v[204:207], v[188:191], v[42:45]
	s_setprio 0
	s_mov_b32 m0, s42
	v_lshl_add_u64 v[208:209], v[212:213], 0, s[86:87]
	s_barrier
	ds_read_b128 v[158:161], v232 offset:49152
	ds_read_b128 v[162:165], v232 offset:50176
	ds_read_b128 v[166:169], v232 offset:51200
	ds_read_b128 v[172:175], v232 offset:52224
	ds_read_b128 v[176:179], v232 offset:53248
	ds_read_b128 v[180:183], v232 offset:54272
	ds_read_b128 v[184:187], v232 offset:55296
	ds_read_b128 v[188:191], v232 offset:56320
	global_load_lds_dwordx4 v[208:209], off
	v_lshl_add_u64 v[208:209], v[214:215], 0, s[86:87]
	s_mov_b32 m0, s43
	s_nop 0
	global_load_lds_dwordx4 v[208:209], off
	s_barrier
; __device__ __forceinline__ float fgelu(float x) { const float u = x * (1.0f + 0.044715f * x * x); return x * fsigmoid(1.59576912f * u); }
; __device__ __forceinline__ int ltid(int sw) { unsigned z = 0u; asm volatile("" : "+s"(sw), "+s"(z)); int t = sw * 64 + (int)__builtin_amdgcn_mbcnt_hi(~0u, __builtin_amdgcn_mbcnt_lo(~0u, z)); asm volatile("" : "+v"(t)); return t; }
; #define PG8_STAGE(bufoff, gbase, voff) do { _Pragma("unroll") for (int _i = 0; _i < 2; ++_i) \
;         __builtin_amdgcn_global_load_lds((const __attribute__((address_space(1))) unsigned*)((const char*)(gbase) + (voff)[_i]), (LAS unsigned*)(lds + (bufoff) + ldsw + _i * 8192), 16, 0, 0); } while (0)
; #define PG8_WAIT_V(n) asm volatile("s_waitcnt vmcnt(" #n ")" ::: "memory")
; #define PG8_WAIT_L(n) asm volatile("s_waitcnt lgkmcnt(" #n ")" ::: "memory")
; #define PG8_BAR __builtin_amdgcn_s_barrier()
; template <class Epi>
; __device__ __forceinline__ void gemm_phase(LAS unsigned char* lds, const Gemm g, const StaticOrder& S_in, const Epi& E, int sw) {
;     ...
;             PG8_BAR; PG8_WAIT_L(0); PG8_MMA(1, 0, At, B0); PG8_BAR; PG8_SCHED;
;             PG8_STAGE(PG8_SB(1, 1), b3 + hstepB, voffB);
;             PG8_WAIT_V(6); PG8_BAR; PG8_MMA(1, 1, At, B1); PG8_BAR;
;     EPI_ZERO_INIT
;     __device__ __forceinline__ void operator()(AccRef acc, const Unit& u, int sw) const {
;         const int tid_ = ltid(sw), lane_ = tid_ & 63, wr = sw >> 2, wc = sw & 3, fr = lane_ & 15, fq = lane_ >> 4;
;         const int row0 = u.pm * BM + wr * 64 + fr, col0 = u.pn * BM + wc * 32 + 8 * fq;
; #pragma unroll
;         for (int bj = 0; bj < 2; ++bj) {
;             float cs[2][4], cq[2][4];
; #pragma unroll
;             for (int n = 0; n < 2; ++n)
; #pragma unroll
;                 for (int j = 0; j < 4; ++j) { cs[n][j] = 0.f; cq[n][j] = 0.f; }
; #pragma unroll
;             for (int ai = 0; ai < 2; ++ai)
; #pragma unroll
;                 for (int m = 0; m < 4; ++m) { bf16_t* rowp = Vt + ((size_t)(2 * u.pn + bj) * E + (row0 + ai * HALF + m * 16)) * 128 + wc * 32 + 8 * fq;
;                     f32x4 v0 = acc[ai][bj][m][0], v1 = acc[ai][bj][m][1];
; #pragma unroll
;                     for (int j = 0; j < 4; ++j) { v0[j] = fgelu(v0[j]); v1[j] = fgelu(v1[j]);
;                         cs[0][j] += v0[j]; cq[0][j] += v0[j] * v0[j]; cs[1][j] += v1[j]; cq[1][j] += v1[j] * v1[j]; }
	s_waitcnt lgkmcnt(0)
	s_setprio 1
	s_waitcnt lgkmcnt(0)
	v_mfma_f32_16x16x32_bf16 v[78:81], v[142:145], v[158:161], v[78:81]
	v_mfma_f32_16x16x32_bf16 v[102:105], v[150:153], v[158:161], v[102:105]
	v_mfma_f32_16x16x32_bf16 v[74:77], v[142:145], v[166:169], v[74:77]
	v_mfma_f32_16x16x32_bf16 v[98:101], v[150:153], v[166:169], v[98:101]
	v_mfma_f32_16x16x32_bf16 v[70:73], v[142:145], v[176:179], v[70:73]
	v_mfma_f32_16x16x32_bf16 v[94:97], v[150:153], v[176:179], v[94:97]
	v_mfma_f32_16x16x32_bf16 v[66:69], v[142:145], v[184:187], v[66:69]
	v_mfma_f32_16x16x32_bf16 v[82:85], v[150:153], v[184:187], v[82:85]
	v_mfma_f32_16x16x32_bf16 v[78:81], v[146:149], v[162:165], v[78:81]
	v_mfma_f32_16x16x32_bf16 v[102:105], v[154:157], v[162:165], v[102:105]
	v_mfma_f32_16x16x32_bf16 v[74:77], v[146:149], v[172:175], v[74:77]
	v_mfma_f32_16x16x32_bf16 v[98:101], v[154:157], v[172:175], v[98:101]
	v_mfma_f32_16x16x32_bf16 v[70:73], v[146:149], v[180:183], v[70:73]
	v_mfma_f32_16x16x32_bf16 v[94:97], v[154:157], v[180:183], v[94:97]
	v_mfma_f32_16x16x32_bf16 v[66:69], v[146:149], v[188:191], v[66:69]
	v_mfma_f32_16x16x32_bf16 v[82:85], v[154:157], v[188:191], v[82:85]
	s_setprio 0
	s_barrier
	s_add_u32 s20, s20, 0x40080
	s_addc_u32 s21, s21, 0
	s_add_i32 s22, s22, s29
	v_lshl_add_u64 v[142:143], s[20:21], 0, v[132:133]
	s_mov_b32 m0, s22
	s_nop 0
	global_load_lds_dwordx4 v[142:143], off
	v_lshl_add_u64 v[142:143], s[20:21], 0, v[136:137]
	s_add_i32 m0, s22, 0x2000
	s_nop 0
	global_load_lds_dwordx4 v[142:143], off
	s_waitcnt vmcnt(6)
	s_barrier
	s_setprio 1
	v_mfma_f32_16x16x32_bf16 v[14:17], v[192:195], v[158:161], v[14:17]
	v_mfma_f32_16x16x32_bf16 v[38:41], v[200:203], v[158:161], v[38:41]
	v_mfma_f32_16x16x32_bf16 v[10:13], v[192:195], v[166:169], v[10:13]
	v_mfma_f32_16x16x32_bf16 v[34:37], v[200:203], v[166:169], v[34:37]
	v_mfma_f32_16x16x32_bf16 v[6:9], v[192:195], v[176:179], v[6:9]
	v_mfma_f32_16x16x32_bf16 v[30:33], v[200:203], v[176:179], v[30:33]
	v_mfma_f32_16x16x32_bf16 v[2:5], v[192:195], v[184:187], v[2:5]
	v_mfma_f32_16x16x32_bf16 v[18:21], v[200:203], v[184:187], v[18:21]
	v_mfma_f32_16x16x32_bf16 v[14:17], v[196:199], v[162:165], v[14:17]
	v_mfma_f32_16x16x32_bf16 v[38:41], v[204:207], v[162:165], v[38:41]
	v_mfma_f32_16x16x32_bf16 v[10:13], v[196:199], v[172:175], v[10:13]
	v_mfma_f32_16x16x32_bf16 v[34:37], v[204:207], v[172:175], v[34:37]
	v_mfma_f32_16x16x32_bf16 v[6:9], v[196:199], v[180:183], v[6:9]
	v_mfma_f32_16x16x32_bf16 v[30:33], v[204:207], v[180:183], v[30:33]
	v_mfma_f32_16x16x32_bf16 v[2:5], v[196:199], v[188:191], v[2:5]
	v_mfma_f32_16x16x32_bf16 v[18:21], v[204:207], v[188:191], v[18:21]
	s_setprio 0
	s_add_i32 s50, s50, 2
	s_add_u32 s0, s0, 0x100
	s_addc_u32 s1, s1, 0
	s_add_u32 s48, s48, 0x100
	s_addc_u32 s49, s49, 0
	s_cmp_gt_u32 s50, 13
	s_barrier
	s_cbranch_scc0 .LBB0_771
	v_readlane_b32 s7, v255, 6
	v_readlane_b32 s1, v255, 7
	v_mbcnt_lo_u32_b32 v224, -1, 0
	v_mbcnt_hi_u32_b32 v224, -1, v224
	v_lshl_add_u32 v224, s75, 6, v224
	s_nop 3
	s_lshl_b32 s0, s18, 8
	s_add_i32 s0, s0, s1
	v_and_b32_e32 v220, 15, v224
	v_lshrrev_b32_e32 v221, 1, v224
	v_and_b32_e32 v221, 24, v221
	v_or_b32_e32 v224, s0, v220
	v_lshlrev_b32_e32 v212, 8, v224
	v_lshl_add_u32 v212, v221, 1, v212
	v_add_u32_e32 v212, s90, v212
	s_lshl_b32 s0, s18, 1
	s_add_i32 s0, s0, s7
	s_ashr_i32 s1, s0, 31
	s_lshl_b64 s[0:1], s[0:1], 18
	s_add_u32 s0, s40, s0
	s_addc_u32 s1, s41, s1
	s_lshl_b32 s18, s16, 1
	s_ashr_i32 s19, s18, 31
	s_lshl_b64 s[18:19], s[18:19], 19
	s_add_u32 s18, s38, s18
	s_addc_u32 s19, s39, s19
	s_add_u32 s20, s18, 0x80000
	s_addc_u32 s21, s19, 0
	s_lshl_b32 s7, s16, 8
	s_or_b32 s7, s7, s85
	v_or_b32_e32 v222, s7, v221
	v_lshlrev_b32_e32 v222, 3, v222
	s_mov_b64 s[16:17], s[0:1]
	s_mov_b32 s0, 0xbdd2d3e7
	v_mov_b32_e32 v223, s84
	v_cmp_eq_u32_e32 vcc, 0, v220
	v_add_u32_e32 v213, 0x1000, v212
	v_add_u32_e32 v214, 0x2000, v212
	v_add_u32_e32 v215, 0x3000, v212
	v_add_u32_e32 v216, 0x8000, v212
	v_add_u32_e32 v217, 0x9000, v212
	v_add_u32_e32 v218, 0xa000, v212
	v_add_u32_e32 v219, 0xb000, v212
	v_mov_b32_e32 v172, 0
	v_mov_b32_e32 v173, 0
	v_mov_b32_e32 v174, 0
	v_mov_b32_e32 v175, 0
	v_mov_b32_e32 v176, 0
	v_mov_b32_e32 v177, 0
	v_mov_b32_e32 v178, 0
	v_mov_b32_e32 v179, 0
	v_mov_b32_e32 v180, 0
	v_mov_b32_e32 v181, 0
	v_mov_b32_e32 v182, 0
	v_mov_b32_e32 v183, 0
	v_mov_b32_e32 v184, 0
	v_mov_b32_e32 v185, 0
	v_mov_b32_e32 v186, 0
	v_mov_b32_e32 v187, 0
	v_mul_f32_e32 v188, v126, v126
	v_mul_f32_e32 v189, v127, v127
	v_mul_f32_e32 v190, v128, v128
	v_mul_f32_e32 v191, v129, v129
	v_mul_f32_e32 v192, v122, v122
	v_mul_f32_e32 v193, v123, v123
	v_mul_f32_e32 v194, v124, v124
	v_mul_f32_e32 v195, v125, v125
	v_fma_f32 v188, v188, s0, v223
	v_fma_f32 v189, v189, s0, v223
	v_fma_f32 v190, v190, s0, v223
	v_fma_f32 v191, v191, s0, v223
	v_fma_f32 v192, v192, s0, v223
	v_fma_f32 v193, v193, s0, v223
	v_fma_f32 v194, v194, s0, v223
	v_fma_f32 v195, v195, s0, v223
	v_mul_f32_e32 v188, v188, v126
	v_mul_f32_e32 v189, v189, v127
	v_mul_f32_e32 v190, v190, v128
	v_mul_f32_e32 v191, v191, v129
	v_mul_f32_e32 v192, v192, v122
	v_mul_f32_e32 v193, v193, v123
	v_mul_f32_e32 v194, v194, v124
	v_mul_f32_e32 v195, v195, v125
	v_exp_f32_e32 v188, v188
	v_exp_f32_e32 v189, v189
	v_exp_f32_e32 v190, v190
	v_exp_f32_e32 v191, v191
	v_exp_f32_e32 v192, v192
	v_exp_f32_e32 v193, v193
	v_exp_f32_e32 v194, v194
	v_exp_f32_e32 v195, v195
	v_add_f32_e32 v188, 1.0, v188
	v_add_f32_e32 v189, 1.0, v189
	v_add_f32_e32 v190, 1.0, v190
	v_add_f32_e32 v191, 1.0, v191
	v_add_f32_e32 v192, 1.0, v192
	v_add_f32_e32 v193, 1.0, v193
	v_add_f32_e32 v194, 1.0, v194
; __device__ __forceinline__ unsigned cvt_pk_bf16(float lo, float hi) { unsigned r; asm volatile("v_cvt_pk_bf16_f32 %0, %1, %2" : "=v"(r) : "v"(lo), "v"(hi)); return r; }
; __device__ __forceinline__ float fgelu(float x) { const float u = x * (1.0f + 0.044715f * x * x); return x * fsigmoid(1.59576912f * u); }
;     EPI_ZERO_INIT
;     __device__ __forceinline__ void operator()(AccRef acc, const Unit& u, int sw) const {
;     ...
;             for (int ai = 0; ai < 2; ++ai)
; #pragma unroll
;                 for (int m = 0; m < 4; ++m) { bf16_t* rowp = Vt + ((size_t)(2 * u.pn + bj) * E + (row0 + ai * HALF + m * 16)) * 128 + wc * 32 + 8 * fq;
;                     f32x4 v0 = acc[ai][bj][m][0], v1 = acc[ai][bj][m][1];
; #pragma unroll
;                     for (int j = 0; j < 4; ++j) { v0[j] = fgelu(v0[j]); v1[j] = fgelu(v1[j]);
;                         cs[0][j] += v0[j]; cq[0][j] += v0[j] * v0[j]; cs[1][j] += v1[j]; cq[1][j] += v1[j] * v1[j]; }
;                     u32x4 w; w.x = cvt_pk_bf16(v0[0], v0[1]); w.y = cvt_pk_bf16(v0[2], v0[3]); w.z = cvt_pk_bf16(v1[0], v1[1]); w.w = cvt_pk_bf16(v1[2], v1[3]);
;                     *(u32x4*)rowp = w; }
	v_add_f32_e32 v195, 1.0, v195
	v_rcp_f32_e32 v188, v188
	v_rcp_f32_e32 v189, v189
	v_rcp_f32_e32 v190, v190
	v_rcp_f32_e32 v191, v191
	v_rcp_f32_e32 v192, v192
	v_rcp_f32_e32 v193, v193
	v_rcp_f32_e32 v194, v194
	v_rcp_f32_e32 v195, v195
	v_mul_f32_e32 v196, v126, v188
	v_mul_f32_e32 v197, v127, v189
	v_mul_f32_e32 v198, v128, v190
	v_mul_f32_e32 v199, v129, v191
	v_mul_f32_e32 v200, v122, v192
	v_mul_f32_e32 v201, v123, v193
	v_mul_f32_e32 v202, v124, v194
	v_mul_f32_e32 v203, v125, v195
	v_add_f32_e32 v172, v172, v196
	v_add_f32_e32 v174, v174, v197
	v_add_f32_e32 v176, v176, v198
	v_add_f32_e32 v178, v178, v199
	v_add_f32_e32 v180, v180, v200
	v_add_f32_e32 v182, v182, v201
	v_add_f32_e32 v184, v184, v202
	v_add_f32_e32 v186, v186, v203
	v_fmac_f32_e32 v173, v196, v196
	v_fmac_f32_e32 v175, v197, v197
	v_fmac_f32_e32 v177, v198, v198
	v_fmac_f32_e32 v179, v199, v199
	v_fmac_f32_e32 v181, v200, v200
	v_fmac_f32_e32 v183, v201, v201
	v_fmac_f32_e32 v185, v202, v202
	v_fmac_f32_e32 v187, v203, v203
	v_cvt_pk_bf16_f32 v204, v196, v197
	v_cvt_pk_bf16_f32 v205, v198, v199
	v_cvt_pk_bf16_f32 v206, v200, v201
	v_cvt_pk_bf16_f32 v207, v202, v203
	global_store_dwordx4 v212, v[204:207], s[18:19]
	v_mul_f32_e32 v188, v118, v118
	v_mul_f32_e32 v189, v119, v119
	v_mul_f32_e32 v190, v120, v120
	v_mul_f32_e32 v191, v121, v121
	v_mul_f32_e32 v192, v114, v114
	v_mul_f32_e32 v193, v115, v115
	v_mul_f32_e32 v194, v116, v116
	v_mul_f32_e32 v195, v117, v117
	v_fma_f32 v188, v188, s0, v223
	v_fma_f32 v189, v189, s0, v223
	v_fma_f32 v190, v190, s0, v223
	v_fma_f32 v191, v191, s0, v223
	v_fma_f32 v192, v192, s0, v223
	v_fma_f32 v193, v193, s0, v223
	v_fma_f32 v194, v194, s0, v223
	v_fma_f32 v195, v195, s0, v223
	v_mul_f32_e32 v188, v188, v118
	v_mul_f32_e32 v189, v189, v119
	v_mul_f32_e32 v190, v190, v120
	v_mul_f32_e32 v191, v191, v121
	v_mul_f32_e32 v192, v192, v114
	v_mul_f32_e32 v193, v193, v115
	v_mul_f32_e32 v194, v194, v116
	v_mul_f32_e32 v195, v195, v117
	v_exp_f32_e32 v188, v188
	v_exp_f32_e32 v189, v189
	v_exp_f32_e32 v190, v190
	v_exp_f32_e32 v191, v191
	v_exp_f32_e32 v192, v192
	v_exp_f32_e32 v193, v193
	v_exp_f32_e32 v194, v194
	v_exp_f32_e32 v195, v195
	v_add_f32_e32 v188, 1.0, v188
	v_add_f32_e32 v189, 1.0, v189
	v_add_f32_e32 v190, 1.0, v190
	v_add_f32_e32 v191, 1.0, v191
	v_add_f32_e32 v192, 1.0, v192
	v_add_f32_e32 v193, 1.0, v193
	v_add_f32_e32 v194, 1.0, v194
	v_add_f32_e32 v195, 1.0, v195
	v_rcp_f32_e32 v188, v188
	v_rcp_f32_e32 v189, v189
	v_rcp_f32_e32 v190, v190
	v_rcp_f32_e32 v191, v191
	v_rcp_f32_e32 v192, v192
	v_rcp_f32_e32 v193, v193
	v_rcp_f32_e32 v194, v194
	v_rcp_f32_e32 v195, v195
	v_mul_f32_e32 v196, v118, v188
	v_mul_f32_e32 v197, v119, v189
	v_mul_f32_e32 v198, v120, v190
	v_mul_f32_e32 v199, v121, v191
	v_mul_f32_e32 v200, v114, v192
	v_mul_f32_e32 v201, v115, v193
	v_mul_f32_e32 v202, v116, v194
	v_mul_f32_e32 v203, v117, v195
	v_add_f32_e32 v172, v172, v196
	v_add_f32_e32 v174, v174, v197
	v_add_f32_e32 v176, v176, v198
	v_add_f32_e32 v178, v178, v199
	v_add_f32_e32 v180, v180, v200
	v_add_f32_e32 v182, v182, v201
	v_add_f32_e32 v184, v184, v202
	v_add_f32_e32 v186, v186, v203
	v_fmac_f32_e32 v173, v196, v196
	v_fmac_f32_e32 v175, v197, v197
	v_fmac_f32_e32 v177, v198, v198
	v_fmac_f32_e32 v179, v199, v199
	v_fmac_f32_e32 v181, v200, v200
	v_fmac_f32_e32 v183, v201, v201
	v_fmac_f32_e32 v185, v202, v202
	v_fmac_f32_e32 v187, v203, v203
	v_cvt_pk_bf16_f32 v208, v196, v197
	v_cvt_pk_bf16_f32 v209, v198, v199
	v_cvt_pk_bf16_f32 v210, v200, v201
	v_cvt_pk_bf16_f32 v211, v202, v203
	global_store_dwordx4 v213, v[208:211], s[18:19]
	v_mul_f32_e32 v188, v90, v90
	v_mul_f32_e32 v189, v91, v91
	v_mul_f32_e32 v190, v92, v92
	v_mul_f32_e32 v191, v93, v93
	v_mul_f32_e32 v192, v110, v110
	v_mul_f32_e32 v193, v111, v111
	v_mul_f32_e32 v194, v112, v112
	v_mul_f32_e32 v195, v113, v113
	v_fma_f32 v188, v188, s0, v223
	v_fma_f32 v189, v189, s0, v223
	v_fma_f32 v190, v190, s0, v223
	v_fma_f32 v191, v191, s0, v223
	v_fma_f32 v192, v192, s0, v223
	v_fma_f32 v193, v193, s0, v223
	v_fma_f32 v194, v194, s0, v223
	v_fma_f32 v195, v195, s0, v223
	v_mul_f32_e32 v188, v188, v90
	v_mul_f32_e32 v189, v189, v91
	v_mul_f32_e32 v190, v190, v92
	v_mul_f32_e32 v191, v191, v93
	v_mul_f32_e32 v192, v192, v110
	v_mul_f32_e32 v193, v193, v111
	v_mul_f32_e32 v194, v194, v112
	v_mul_f32_e32 v195, v195, v113
	v_exp_f32_e32 v188, v188
	v_exp_f32_e32 v189, v189
	v_exp_f32_e32 v190, v190
	v_exp_f32_e32 v191, v191
	v_exp_f32_e32 v192, v192
	v_exp_f32_e32 v193, v193
	v_exp_f32_e32 v194, v194
	v_exp_f32_e32 v195, v195
	v_add_f32_e32 v188, 1.0, v188
	v_add_f32_e32 v189, 1.0, v189
	v_add_f32_e32 v190, 1.0, v190
	v_add_f32_e32 v191, 1.0, v191
	v_add_f32_e32 v192, 1.0, v192
	v_add_f32_e32 v193, 1.0, v193
	v_add_f32_e32 v194, 1.0, v194
	v_add_f32_e32 v195, 1.0, v195
	v_rcp_f32_e32 v188, v188
	v_rcp_f32_e32 v189, v189
	v_rcp_f32_e32 v190, v190
	v_rcp_f32_e32 v191, v191
	v_rcp_f32_e32 v192, v192
	v_rcp_f32_e32 v193, v193
	v_rcp_f32_e32 v194, v194
	v_rcp_f32_e32 v195, v195
	v_mul_f32_e32 v196, v90, v188
	v_mul_f32_e32 v197, v91, v189
	v_mul_f32_e32 v198, v92, v190
	v_mul_f32_e32 v199, v93, v191
	v_mul_f32_e32 v200, v110, v192
	v_mul_f32_e32 v201, v111, v193
	v_mul_f32_e32 v202, v112, v194
	v_mul_f32_e32 v203, v113, v195
	v_add_f32_e32 v172, v172, v196
	v_add_f32_e32 v174, v174, v197
	v_add_f32_e32 v176, v176, v198
	v_add_f32_e32 v178, v178, v199
	v_add_f32_e32 v180, v180, v200
	v_add_f32_e32 v182, v182, v201
	v_add_f32_e32 v184, v184, v202
	v_add_f32_e32 v186, v186, v203
	v_fmac_f32_e32 v173, v196, v196
	v_fmac_f32_e32 v175, v197, v197
	v_fmac_f32_e32 v177, v198, v198
; __device__ __forceinline__ unsigned cvt_pk_bf16(float lo, float hi) { unsigned r; asm volatile("v_cvt_pk_bf16_f32 %0, %1, %2" : "=v"(r) : "v"(lo), "v"(hi)); return r; }
; __device__ __forceinline__ float fgelu(float x) { const float u = x * (1.0f + 0.044715f * x * x); return x * fsigmoid(1.59576912f * u); }
;     EPI_ZERO_INIT
;     __device__ __forceinline__ void operator()(AccRef acc, const Unit& u, int sw) const {
;     ...
;             for (int ai = 0; ai < 2; ++ai)
; #pragma unroll
;                 for (int m = 0; m < 4; ++m) { bf16_t* rowp = Vt + ((size_t)(2 * u.pn + bj) * E + (row0 + ai * HALF + m * 16)) * 128 + wc * 32 + 8 * fq;
;                     f32x4 v0 = acc[ai][bj][m][0], v1 = acc[ai][bj][m][1];
; #pragma unroll
;                     for (int j = 0; j < 4; ++j) { v0[j] = fgelu(v0[j]); v1[j] = fgelu(v1[j]);
;                         cs[0][j] += v0[j]; cq[0][j] += v0[j] * v0[j]; cs[1][j] += v1[j]; cq[1][j] += v1[j] * v1[j]; }
;                     u32x4 w; w.x = cvt_pk_bf16(v0[0], v0[1]); w.y = cvt_pk_bf16(v0[2], v0[3]); w.z = cvt_pk_bf16(v1[0], v1[1]); w.w = cvt_pk_bf16(v1[2], v1[3]);
;                     *(u32x4*)rowp = w; }
	v_fmac_f32_e32 v179, v199, v199
	v_fmac_f32_e32 v181, v200, v200
	v_fmac_f32_e32 v183, v201, v201
	v_fmac_f32_e32 v185, v202, v202
	v_fmac_f32_e32 v187, v203, v203
	v_cvt_pk_bf16_f32 v204, v196, v197
	v_cvt_pk_bf16_f32 v205, v198, v199
	v_cvt_pk_bf16_f32 v206, v200, v201
	v_cvt_pk_bf16_f32 v207, v202, v203
	global_store_dwordx4 v214, v[204:207], s[18:19]
	v_mul_f32_e32 v188, v86, v86
	v_mul_f32_e32 v189, v87, v87
	v_mul_f32_e32 v190, v88, v88
	v_mul_f32_e32 v191, v89, v89
	v_mul_f32_e32 v192, v106, v106
	v_mul_f32_e32 v193, v107, v107
	v_mul_f32_e32 v194, v108, v108
	v_mul_f32_e32 v195, v109, v109
	v_fma_f32 v188, v188, s0, v223
	v_fma_f32 v189, v189, s0, v223
	v_fma_f32 v190, v190, s0, v223
	v_fma_f32 v191, v191, s0, v223
	v_fma_f32 v192, v192, s0, v223
	v_fma_f32 v193, v193, s0, v223
	v_fma_f32 v194, v194, s0, v223
	v_fma_f32 v195, v195, s0, v223
	v_mul_f32_e32 v188, v188, v86
	v_mul_f32_e32 v189, v189, v87
	v_mul_f32_e32 v190, v190, v88
	v_mul_f32_e32 v191, v191, v89
	v_mul_f32_e32 v192, v192, v106
	v_mul_f32_e32 v193, v193, v107
	v_mul_f32_e32 v194, v194, v108
	v_mul_f32_e32 v195, v195, v109
	v_exp_f32_e32 v188, v188
	v_exp_f32_e32 v189, v189
	v_exp_f32_e32 v190, v190
	v_exp_f32_e32 v191, v191
	v_exp_f32_e32 v192, v192
	v_exp_f32_e32 v193, v193
	v_exp_f32_e32 v194, v194
	v_exp_f32_e32 v195, v195
	v_add_f32_e32 v188, 1.0, v188
	v_add_f32_e32 v189, 1.0, v189
	v_add_f32_e32 v190, 1.0, v190
	v_add_f32_e32 v191, 1.0, v191
	v_add_f32_e32 v192, 1.0, v192
	v_add_f32_e32 v193, 1.0, v193
	v_add_f32_e32 v194, 1.0, v194
	v_add_f32_e32 v195, 1.0, v195
	v_rcp_f32_e32 v188, v188
	v_rcp_f32_e32 v189, v189
	v_rcp_f32_e32 v190, v190
	v_rcp_f32_e32 v191, v191
	v_rcp_f32_e32 v192, v192
	v_rcp_f32_e32 v193, v193
	v_rcp_f32_e32 v194, v194
	v_rcp_f32_e32 v195, v195
	v_mul_f32_e32 v196, v86, v188
	v_mul_f32_e32 v197, v87, v189
	v_mul_f32_e32 v198, v88, v190
	v_mul_f32_e32 v199, v89, v191
	v_mul_f32_e32 v200, v106, v192
	v_mul_f32_e32 v201, v107, v193
	v_mul_f32_e32 v202, v108, v194
	v_mul_f32_e32 v203, v109, v195
	v_add_f32_e32 v172, v172, v196
	v_add_f32_e32 v174, v174, v197
	v_add_f32_e32 v176, v176, v198
	v_add_f32_e32 v178, v178, v199
	v_add_f32_e32 v180, v180, v200
	v_add_f32_e32 v182, v182, v201
	v_add_f32_e32 v184, v184, v202
	v_add_f32_e32 v186, v186, v203
	v_fmac_f32_e32 v173, v196, v196
	v_fmac_f32_e32 v175, v197, v197
	v_fmac_f32_e32 v177, v198, v198
	v_fmac_f32_e32 v179, v199, v199
	v_fmac_f32_e32 v181, v200, v200
	v_fmac_f32_e32 v183, v201, v201
	v_fmac_f32_e32 v185, v202, v202
	v_fmac_f32_e32 v187, v203, v203
	v_cvt_pk_bf16_f32 v208, v196, v197
	v_cvt_pk_bf16_f32 v209, v198, v199
	v_cvt_pk_bf16_f32 v210, v200, v201
	v_cvt_pk_bf16_f32 v211, v202, v203
	global_store_dwordx4 v215, v[208:211], s[18:19]
	v_mul_f32_e32 v188, v78, v78
	v_mul_f32_e32 v189, v79, v79
	v_mul_f32_e32 v190, v80, v80
	v_mul_f32_e32 v191, v81, v81
	v_mul_f32_e32 v192, v102, v102
	v_mul_f32_e32 v193, v103, v103
	v_mul_f32_e32 v194, v104, v104
	v_mul_f32_e32 v195, v105, v105
	v_fma_f32 v188, v188, s0, v223
	v_fma_f32 v189, v189, s0, v223
	v_fma_f32 v190, v190, s0, v223
	v_fma_f32 v191, v191, s0, v223
	v_fma_f32 v192, v192, s0, v223
	v_fma_f32 v193, v193, s0, v223
	v_fma_f32 v194, v194, s0, v223
	v_fma_f32 v195, v195, s0, v223
	v_mul_f32_e32 v188, v188, v78
	v_mul_f32_e32 v189, v189, v79
	v_mul_f32_e32 v190, v190, v80
	v_mul_f32_e32 v191, v191, v81
	v_mul_f32_e32 v192, v192, v102
	v_mul_f32_e32 v193, v193, v103
	v_mul_f32_e32 v194, v194, v104
	v_mul_f32_e32 v195, v195, v105
	v_exp_f32_e32 v188, v188
	v_exp_f32_e32 v189, v189
	v_exp_f32_e32 v190, v190
	v_exp_f32_e32 v191, v191
	v_exp_f32_e32 v192, v192
	v_exp_f32_e32 v193, v193
	v_exp_f32_e32 v194, v194
	v_exp_f32_e32 v195, v195
	v_add_f32_e32 v188, 1.0, v188
	v_add_f32_e32 v189, 1.0, v189
	v_add_f32_e32 v190, 1.0, v190
	v_add_f32_e32 v191, 1.0, v191
	v_add_f32_e32 v192, 1.0, v192
	v_add_f32_e32 v193, 1.0, v193
	v_add_f32_e32 v194, 1.0, v194
	v_add_f32_e32 v195, 1.0, v195
	v_rcp_f32_e32 v188, v188
	v_rcp_f32_e32 v189, v189
	v_rcp_f32_e32 v190, v190
	v_rcp_f32_e32 v191, v191
	v_rcp_f32_e32 v192, v192
	v_rcp_f32_e32 v193, v193
	v_rcp_f32_e32 v194, v194
	v_rcp_f32_e32 v195, v195
	v_mul_f32_e32 v196, v78, v188
	v_mul_f32_e32 v197, v79, v189
	v_mul_f32_e32 v198, v80, v190
	v_mul_f32_e32 v199, v81, v191
	v_mul_f32_e32 v200, v102, v192
	v_mul_f32_e32 v201, v103, v193
	v_mul_f32_e32 v202, v104, v194
	v_mul_f32_e32 v203, v105, v195
	v_add_f32_e32 v172, v172, v196
	v_add_f32_e32 v174, v174, v197
	v_add_f32_e32 v176, v176, v198
	v_add_f32_e32 v178, v178, v199
	v_add_f32_e32 v180, v180, v200
	v_add_f32_e32 v182, v182, v201
	v_add_f32_e32 v184, v184, v202
	v_add_f32_e32 v186, v186, v203
	v_fmac_f32_e32 v173, v196, v196
	v_fmac_f32_e32 v175, v197, v197
	v_fmac_f32_e32 v177, v198, v198
	v_fmac_f32_e32 v179, v199, v199
	v_fmac_f32_e32 v181, v200, v200
	v_fmac_f32_e32 v183, v201, v201
	v_fmac_f32_e32 v185, v202, v202
	v_fmac_f32_e32 v187, v203, v203
	v_cvt_pk_bf16_f32 v204, v196, v197
	v_cvt_pk_bf16_f32 v205, v198, v199
	v_cvt_pk_bf16_f32 v206, v200, v201
	v_cvt_pk_bf16_f32 v207, v202, v203
	global_store_dwordx4 v216, v[204:207], s[18:19]
	v_mul_f32_e32 v188, v74, v74
	v_mul_f32_e32 v189, v75, v75
	v_mul_f32_e32 v190, v76, v76
	v_mul_f32_e32 v191, v77, v77
	v_mul_f32_e32 v192, v98, v98
	v_mul_f32_e32 v193, v99, v99
	v_mul_f32_e32 v194, v100, v100
	v_mul_f32_e32 v195, v101, v101
	v_fma_f32 v188, v188, s0, v223
	v_fma_f32 v189, v189, s0, v223
	v_fma_f32 v190, v190, s0, v223
	v_fma_f32 v191, v191, s0, v223
	v_fma_f32 v192, v192, s0, v223
	v_fma_f32 v193, v193, s0, v223
	v_fma_f32 v194, v194, s0, v223
	v_fma_f32 v195, v195, s0, v223
; __device__ __forceinline__ unsigned cvt_pk_bf16(float lo, float hi) { unsigned r; asm volatile("v_cvt_pk_bf16_f32 %0, %1, %2" : "=v"(r) : "v"(lo), "v"(hi)); return r; }
; __device__ __forceinline__ float fgelu(float x) { const float u = x * (1.0f + 0.044715f * x * x); return x * fsigmoid(1.59576912f * u); }
;     EPI_ZERO_INIT
;     __device__ __forceinline__ void operator()(AccRef acc, const Unit& u, int sw) const {
;     ...
;             for (int ai = 0; ai < 2; ++ai)
; #pragma unroll
;                 for (int m = 0; m < 4; ++m) { bf16_t* rowp = Vt + ((size_t)(2 * u.pn + bj) * E + (row0 + ai * HALF + m * 16)) * 128 + wc * 32 + 8 * fq;
;                     f32x4 v0 = acc[ai][bj][m][0], v1 = acc[ai][bj][m][1];
; #pragma unroll
;                     for (int j = 0; j < 4; ++j) { v0[j] = fgelu(v0[j]); v1[j] = fgelu(v1[j]);
;                         cs[0][j] += v0[j]; cq[0][j] += v0[j] * v0[j]; cs[1][j] += v1[j]; cq[1][j] += v1[j] * v1[j]; }
;                     u32x4 w; w.x = cvt_pk_bf16(v0[0], v0[1]); w.y = cvt_pk_bf16(v0[2], v0[3]); w.z = cvt_pk_bf16(v1[0], v1[1]); w.w = cvt_pk_bf16(v1[2], v1[3]);
;                     *(u32x4*)rowp = w; }
	v_mul_f32_e32 v188, v188, v74
	v_mul_f32_e32 v189, v189, v75
	v_mul_f32_e32 v190, v190, v76
	v_mul_f32_e32 v191, v191, v77
	v_mul_f32_e32 v192, v192, v98
	v_mul_f32_e32 v193, v193, v99
	v_mul_f32_e32 v194, v194, v100
	v_mul_f32_e32 v195, v195, v101
	v_exp_f32_e32 v188, v188
	v_exp_f32_e32 v189, v189
	v_exp_f32_e32 v190, v190
	v_exp_f32_e32 v191, v191
	v_exp_f32_e32 v192, v192
	v_exp_f32_e32 v193, v193
	v_exp_f32_e32 v194, v194
	v_exp_f32_e32 v195, v195
	v_add_f32_e32 v188, 1.0, v188
	v_add_f32_e32 v189, 1.0, v189
	v_add_f32_e32 v190, 1.0, v190
	v_add_f32_e32 v191, 1.0, v191
	v_add_f32_e32 v192, 1.0, v192
	v_add_f32_e32 v193, 1.0, v193
	v_add_f32_e32 v194, 1.0, v194
	v_add_f32_e32 v195, 1.0, v195
	v_rcp_f32_e32 v188, v188
	v_rcp_f32_e32 v189, v189
	v_rcp_f32_e32 v190, v190
	v_rcp_f32_e32 v191, v191
	v_rcp_f32_e32 v192, v192
	v_rcp_f32_e32 v193, v193
	v_rcp_f32_e32 v194, v194
	v_rcp_f32_e32 v195, v195
	v_mul_f32_e32 v196, v74, v188
	v_mul_f32_e32 v197, v75, v189
	v_mul_f32_e32 v198, v76, v190
	v_mul_f32_e32 v199, v77, v191
	v_mul_f32_e32 v200, v98, v192
	v_mul_f32_e32 v201, v99, v193
	v_mul_f32_e32 v202, v100, v194
	v_mul_f32_e32 v203, v101, v195
	v_add_f32_e32 v172, v172, v196
	v_add_f32_e32 v174, v174, v197
	v_add_f32_e32 v176, v176, v198
	v_add_f32_e32 v178, v178, v199
	v_add_f32_e32 v180, v180, v200
	v_add_f32_e32 v182, v182, v201
	v_add_f32_e32 v184, v184, v202
	v_add_f32_e32 v186, v186, v203
	v_fmac_f32_e32 v173, v196, v196
	v_fmac_f32_e32 v175, v197, v197
	v_fmac_f32_e32 v177, v198, v198
	v_fmac_f32_e32 v179, v199, v199
	v_fmac_f32_e32 v181, v200, v200
	v_fmac_f32_e32 v183, v201, v201
	v_fmac_f32_e32 v185, v202, v202
	v_fmac_f32_e32 v187, v203, v203
	v_cvt_pk_bf16_f32 v208, v196, v197
	v_cvt_pk_bf16_f32 v209, v198, v199
	v_cvt_pk_bf16_f32 v210, v200, v201
	v_cvt_pk_bf16_f32 v211, v202, v203
	global_store_dwordx4 v217, v[208:211], s[18:19]
	v_mul_f32_e32 v188, v70, v70
	v_mul_f32_e32 v189, v71, v71
	v_mul_f32_e32 v190, v72, v72
	v_mul_f32_e32 v191, v73, v73
	v_mul_f32_e32 v192, v94, v94
	v_mul_f32_e32 v193, v95, v95
	v_mul_f32_e32 v194, v96, v96
	v_mul_f32_e32 v195, v97, v97
	v_fma_f32 v188, v188, s0, v223
	v_fma_f32 v189, v189, s0, v223
	v_fma_f32 v190, v190, s0, v223
	v_fma_f32 v191, v191, s0, v223
	v_fma_f32 v192, v192, s0, v223
	v_fma_f32 v193, v193, s0, v223
	v_fma_f32 v194, v194, s0, v223
	v_fma_f32 v195, v195, s0, v223
	v_mul_f32_e32 v188, v188, v70
	v_mul_f32_e32 v189, v189, v71
	v_mul_f32_e32 v190, v190, v72
	v_mul_f32_e32 v191, v191, v73
	v_mul_f32_e32 v192, v192, v94
	v_mul_f32_e32 v193, v193, v95
	v_mul_f32_e32 v194, v194, v96
	v_mul_f32_e32 v195, v195, v97
	v_exp_f32_e32 v188, v188
	v_exp_f32_e32 v189, v189
	v_exp_f32_e32 v190, v190
	v_exp_f32_e32 v191, v191
	v_exp_f32_e32 v192, v192
	v_exp_f32_e32 v193, v193
	v_exp_f32_e32 v194, v194
	v_exp_f32_e32 v195, v195
	v_add_f32_e32 v188, 1.0, v188
	v_add_f32_e32 v189, 1.0, v189
	v_add_f32_e32 v190, 1.0, v190
	v_add_f32_e32 v191, 1.0, v191
	v_add_f32_e32 v192, 1.0, v192
	v_add_f32_e32 v193, 1.0, v193
	v_add_f32_e32 v194, 1.0, v194
	v_add_f32_e32 v195, 1.0, v195
	v_rcp_f32_e32 v188, v188
	v_rcp_f32_e32 v189, v189
	v_rcp_f32_e32 v190, v190
	v_rcp_f32_e32 v191, v191
	v_rcp_f32_e32 v192, v192
	v_rcp_f32_e32 v193, v193
	v_rcp_f32_e32 v194, v194
	v_rcp_f32_e32 v195, v195
	v_mul_f32_e32 v196, v70, v188
	v_mul_f32_e32 v197, v71, v189
	v_mul_f32_e32 v198, v72, v190
	v_mul_f32_e32 v199, v73, v191
	v_mul_f32_e32 v200, v94, v192
	v_mul_f32_e32 v201, v95, v193
	v_mul_f32_e32 v202, v96, v194
	v_mul_f32_e32 v203, v97, v195
	v_add_f32_e32 v172, v172, v196
	v_add_f32_e32 v174, v174, v197
	v_add_f32_e32 v176, v176, v198
	v_add_f32_e32 v178, v178, v199
	v_add_f32_e32 v180, v180, v200
	v_add_f32_e32 v182, v182, v201
	v_add_f32_e32 v184, v184, v202
	v_add_f32_e32 v186, v186, v203
	v_fmac_f32_e32 v173, v196, v196
	v_fmac_f32_e32 v175, v197, v197
	v_fmac_f32_e32 v177, v198, v198
	v_fmac_f32_e32 v179, v199, v199
	v_fmac_f32_e32 v181, v200, v200
	v_fmac_f32_e32 v183, v201, v201
	v_fmac_f32_e32 v185, v202, v202
	v_fmac_f32_e32 v187, v203, v203
	v_cvt_pk_bf16_f32 v204, v196, v197
	v_cvt_pk_bf16_f32 v205, v198, v199
	v_cvt_pk_bf16_f32 v206, v200, v201
	v_cvt_pk_bf16_f32 v207, v202, v203
	global_store_dwordx4 v218, v[204:207], s[18:19]
	v_mul_f32_e32 v188, v66, v66
	v_mul_f32_e32 v189, v67, v67
	v_mul_f32_e32 v190, v68, v68
	v_mul_f32_e32 v191, v69, v69
	v_mul_f32_e32 v192, v82, v82
	v_mul_f32_e32 v193, v83, v83
	v_mul_f32_e32 v194, v84, v84
	v_mul_f32_e32 v195, v85, v85
	v_fma_f32 v188, v188, s0, v223
	v_fma_f32 v189, v189, s0, v223
	v_fma_f32 v190, v190, s0, v223
	v_fma_f32 v191, v191, s0, v223
	v_fma_f32 v192, v192, s0, v223
	v_fma_f32 v193, v193, s0, v223
	v_fma_f32 v194, v194, s0, v223
	v_fma_f32 v195, v195, s0, v223
	v_mul_f32_e32 v188, v188, v66
	v_mul_f32_e32 v189, v189, v67
	v_mul_f32_e32 v190, v190, v68
	v_mul_f32_e32 v191, v191, v69
	v_mul_f32_e32 v192, v192, v82
	v_mul_f32_e32 v193, v193, v83
	v_mul_f32_e32 v194, v194, v84
	v_mul_f32_e32 v195, v195, v85
	v_exp_f32_e32 v188, v188
	v_exp_f32_e32 v189, v189
	v_exp_f32_e32 v190, v190
	v_exp_f32_e32 v191, v191
	v_exp_f32_e32 v192, v192
	v_exp_f32_e32 v193, v193
	v_exp_f32_e32 v194, v194
	v_exp_f32_e32 v195, v195
	v_add_f32_e32 v188, 1.0, v188
	v_add_f32_e32 v189, 1.0, v189
	v_add_f32_e32 v190, 1.0, v190
	v_add_f32_e32 v191, 1.0, v191
	v_add_f32_e32 v192, 1.0, v192
	v_add_f32_e32 v193, 1.0, v193
	v_add_f32_e32 v194, 1.0, v194
	v_add_f32_e32 v195, 1.0, v195
	v_rcp_f32_e32 v188, v188
	v_rcp_f32_e32 v189, v189
	v_rcp_f32_e32 v190, v190
	v_rcp_f32_e32 v191, v191
	v_rcp_f32_e32 v192, v192
	v_rcp_f32_e32 v193, v193
	v_rcp_f32_e32 v194, v194
; __device__ __forceinline__ unsigned cvt_pk_bf16(float lo, float hi) { unsigned r; asm volatile("v_cvt_pk_bf16_f32 %0, %1, %2" : "=v"(r) : "v"(lo), "v"(hi)); return r; }
; __device__ __forceinline__ float fgelu(float x) { const float u = x * (1.0f + 0.044715f * x * x); return x * fsigmoid(1.59576912f * u); }
; template <int K> __device__ __forceinline__ float row_ror(float v) { return __int_as_float(__builtin_amdgcn_update_dpp(0, __float_as_int(v), 0x120 + K, 0xF, 0xF, false)); }
;     EPI_ZERO_INIT
;     __device__ __forceinline__ void operator()(AccRef acc, const Unit& u, int sw) const {
;     ...
;             for (int ai = 0; ai < 2; ++ai)
; #pragma unroll
;                 for (int m = 0; m < 4; ++m) { bf16_t* rowp = Vt + ((size_t)(2 * u.pn + bj) * E + (row0 + ai * HALF + m * 16)) * 128 + wc * 32 + 8 * fq;
;                     f32x4 v0 = acc[ai][bj][m][0], v1 = acc[ai][bj][m][1];
; #pragma unroll
;                     for (int j = 0; j < 4; ++j) { v0[j] = fgelu(v0[j]); v1[j] = fgelu(v1[j]);
;                         cs[0][j] += v0[j]; cq[0][j] += v0[j] * v0[j]; cs[1][j] += v1[j]; cq[1][j] += v1[j] * v1[j]; }
;                     u32x4 w; w.x = cvt_pk_bf16(v0[0], v0[1]); w.y = cvt_pk_bf16(v0[2], v0[3]); w.z = cvt_pk_bf16(v1[0], v1[1]); w.w = cvt_pk_bf16(v1[2], v1[3]);
;                     *(u32x4*)rowp = w; }
;             f32x2* sp = VSTAT + (size_t)(u.pm * 2 + wr) * M + col0 + bj * HALF;
; #pragma unroll
;             for (int n = 0; n < 2; ++n)
; #pragma unroll
;                 for (int j = 0; j < 4; ++j) { float s = cs[n][j], q = cq[n][j];
;                     s += row_ror<8>(s); q += row_ror<8>(q); s += row_ror<4>(s); q += row_ror<4>(q);
;                     s += row_ror<2>(s); q += row_ror<2>(q); s += row_ror<1>(s); q += row_ror<1>(q);
;                     if (fr == 0) sp[4 * n + j] = (f32x2){s, q}; }
	v_rcp_f32_e32 v195, v195
	v_mul_f32_e32 v196, v66, v188
	v_mul_f32_e32 v197, v67, v189
	v_mul_f32_e32 v198, v68, v190
	v_mul_f32_e32 v199, v69, v191
	v_mul_f32_e32 v200, v82, v192
	v_mul_f32_e32 v201, v83, v193
	v_mul_f32_e32 v202, v84, v194
	v_mul_f32_e32 v203, v85, v195
	v_add_f32_e32 v172, v172, v196
	v_add_f32_e32 v174, v174, v197
	v_add_f32_e32 v176, v176, v198
	v_add_f32_e32 v178, v178, v199
	v_add_f32_e32 v180, v180, v200
	v_add_f32_e32 v182, v182, v201
	v_add_f32_e32 v184, v184, v202
	v_add_f32_e32 v186, v186, v203
	v_fmac_f32_e32 v173, v196, v196
	v_fmac_f32_e32 v175, v197, v197
	v_fmac_f32_e32 v177, v198, v198
	v_fmac_f32_e32 v179, v199, v199
	v_fmac_f32_e32 v181, v200, v200
	v_fmac_f32_e32 v183, v201, v201
	v_fmac_f32_e32 v185, v202, v202
	v_fmac_f32_e32 v187, v203, v203
	v_cvt_pk_bf16_f32 v208, v196, v197
	v_cvt_pk_bf16_f32 v209, v198, v199
	v_cvt_pk_bf16_f32 v210, v200, v201
	v_cvt_pk_bf16_f32 v211, v202, v203
	global_store_dwordx4 v219, v[208:211], s[18:19]
	v_add_f32_dpp v172, v172, v172 row_ror:8 row_mask:0xf bank_mask:0xf
	v_add_f32_dpp v173, v173, v173 row_ror:8 row_mask:0xf bank_mask:0xf
	v_add_f32_dpp v174, v174, v174 row_ror:8 row_mask:0xf bank_mask:0xf
	v_add_f32_dpp v175, v175, v175 row_ror:8 row_mask:0xf bank_mask:0xf
	v_add_f32_dpp v176, v176, v176 row_ror:8 row_mask:0xf bank_mask:0xf
	v_add_f32_dpp v177, v177, v177 row_ror:8 row_mask:0xf bank_mask:0xf
	v_add_f32_dpp v178, v178, v178 row_ror:8 row_mask:0xf bank_mask:0xf
	v_add_f32_dpp v179, v179, v179 row_ror:8 row_mask:0xf bank_mask:0xf
	v_add_f32_dpp v180, v180, v180 row_ror:8 row_mask:0xf bank_mask:0xf
	v_add_f32_dpp v181, v181, v181 row_ror:8 row_mask:0xf bank_mask:0xf
	v_add_f32_dpp v182, v182, v182 row_ror:8 row_mask:0xf bank_mask:0xf
	v_add_f32_dpp v183, v183, v183 row_ror:8 row_mask:0xf bank_mask:0xf
	v_add_f32_dpp v184, v184, v184 row_ror:8 row_mask:0xf bank_mask:0xf
	v_add_f32_dpp v185, v185, v185 row_ror:8 row_mask:0xf bank_mask:0xf
	v_add_f32_dpp v186, v186, v186 row_ror:8 row_mask:0xf bank_mask:0xf
	v_add_f32_dpp v187, v187, v187 row_ror:8 row_mask:0xf bank_mask:0xf
	v_add_f32_dpp v172, v172, v172 row_ror:4 row_mask:0xf bank_mask:0xf
	v_add_f32_dpp v173, v173, v173 row_ror:4 row_mask:0xf bank_mask:0xf
	v_add_f32_dpp v174, v174, v174 row_ror:4 row_mask:0xf bank_mask:0xf
	v_add_f32_dpp v175, v175, v175 row_ror:4 row_mask:0xf bank_mask:0xf
	v_add_f32_dpp v176, v176, v176 row_ror:4 row_mask:0xf bank_mask:0xf
	v_add_f32_dpp v177, v177, v177 row_ror:4 row_mask:0xf bank_mask:0xf
	v_add_f32_dpp v178, v178, v178 row_ror:4 row_mask:0xf bank_mask:0xf
	v_add_f32_dpp v179, v179, v179 row_ror:4 row_mask:0xf bank_mask:0xf
	v_add_f32_dpp v180, v180, v180 row_ror:4 row_mask:0xf bank_mask:0xf
	v_add_f32_dpp v181, v181, v181 row_ror:4 row_mask:0xf bank_mask:0xf
	v_add_f32_dpp v182, v182, v182 row_ror:4 row_mask:0xf bank_mask:0xf
	v_add_f32_dpp v183, v183, v183 row_ror:4 row_mask:0xf bank_mask:0xf
	v_add_f32_dpp v184, v184, v184 row_ror:4 row_mask:0xf bank_mask:0xf
	v_add_f32_dpp v185, v185, v185 row_ror:4 row_mask:0xf bank_mask:0xf
	v_add_f32_dpp v186, v186, v186 row_ror:4 row_mask:0xf bank_mask:0xf
	v_add_f32_dpp v187, v187, v187 row_ror:4 row_mask:0xf bank_mask:0xf
	v_add_f32_dpp v172, v172, v172 row_ror:2 row_mask:0xf bank_mask:0xf
	v_add_f32_dpp v173, v173, v173 row_ror:2 row_mask:0xf bank_mask:0xf
	v_add_f32_dpp v174, v174, v174 row_ror:2 row_mask:0xf bank_mask:0xf
	v_add_f32_dpp v175, v175, v175 row_ror:2 row_mask:0xf bank_mask:0xf
	v_add_f32_dpp v176, v176, v176 row_ror:2 row_mask:0xf bank_mask:0xf
	v_add_f32_dpp v177, v177, v177 row_ror:2 row_mask:0xf bank_mask:0xf
	v_add_f32_dpp v178, v178, v178 row_ror:2 row_mask:0xf bank_mask:0xf
	v_add_f32_dpp v179, v179, v179 row_ror:2 row_mask:0xf bank_mask:0xf
	v_add_f32_dpp v180, v180, v180 row_ror:2 row_mask:0xf bank_mask:0xf
	v_add_f32_dpp v181, v181, v181 row_ror:2 row_mask:0xf bank_mask:0xf
	v_add_f32_dpp v182, v182, v182 row_ror:2 row_mask:0xf bank_mask:0xf
	v_add_f32_dpp v183, v183, v183 row_ror:2 row_mask:0xf bank_mask:0xf
	v_add_f32_dpp v184, v184, v184 row_ror:2 row_mask:0xf bank_mask:0xf
	v_add_f32_dpp v185, v185, v185 row_ror:2 row_mask:0xf bank_mask:0xf
	v_add_f32_dpp v186, v186, v186 row_ror:2 row_mask:0xf bank_mask:0xf
	v_add_f32_dpp v187, v187, v187 row_ror:2 row_mask:0xf bank_mask:0xf
	v_add_f32_dpp v172, v172, v172 row_ror:1 row_mask:0xf bank_mask:0xf
	v_add_f32_dpp v173, v173, v173 row_ror:1 row_mask:0xf bank_mask:0xf
	v_add_f32_dpp v174, v174, v174 row_ror:1 row_mask:0xf bank_mask:0xf
	v_add_f32_dpp v175, v175, v175 row_ror:1 row_mask:0xf bank_mask:0xf
	v_add_f32_dpp v176, v176, v176 row_ror:1 row_mask:0xf bank_mask:0xf
	v_add_f32_dpp v177, v177, v177 row_ror:1 row_mask:0xf bank_mask:0xf
	v_add_f32_dpp v178, v178, v178 row_ror:1 row_mask:0xf bank_mask:0xf
	v_add_f32_dpp v179, v179, v179 row_ror:1 row_mask:0xf bank_mask:0xf
	v_add_f32_dpp v180, v180, v180 row_ror:1 row_mask:0xf bank_mask:0xf
	v_add_f32_dpp v181, v181, v181 row_ror:1 row_mask:0xf bank_mask:0xf
	v_add_f32_dpp v182, v182, v182 row_ror:1 row_mask:0xf bank_mask:0xf
	v_add_f32_dpp v183, v183, v183 row_ror:1 row_mask:0xf bank_mask:0xf
	v_add_f32_dpp v184, v184, v184 row_ror:1 row_mask:0xf bank_mask:0xf
	v_add_f32_dpp v185, v185, v185 row_ror:1 row_mask:0xf bank_mask:0xf
	v_add_f32_dpp v186, v186, v186 row_ror:1 row_mask:0xf bank_mask:0xf
	v_add_f32_dpp v187, v187, v187 row_ror:1 row_mask:0xf bank_mask:0xf
	s_nop 1
	s_mov_b64 exec, vcc
	global_store_dwordx4 v222, v[172:175], s[16:17]
	global_store_dwordx4 v222, v[176:179], s[16:17] offset:16
	global_store_dwordx4 v222, v[180:183], s[16:17] offset:32
	global_store_dwordx4 v222, v[184:187], s[16:17] offset:48
; __device__ __forceinline__ unsigned cvt_pk_bf16(float lo, float hi) { unsigned r; asm volatile("v_cvt_pk_bf16_f32 %0, %1, %2" : "=v"(r) : "v"(lo), "v"(hi)); return r; }
; __device__ __forceinline__ float fgelu(float x) { const float u = x * (1.0f + 0.044715f * x * x); return x * fsigmoid(1.59576912f * u); }
;     EPI_ZERO_INIT
;     __device__ __forceinline__ void operator()(AccRef acc, const Unit& u, int sw) const {
;     ...
;         for (int bj = 0; bj < 2; ++bj) {
;             float cs[2][4], cq[2][4];
; #pragma unroll
;             for (int n = 0; n < 2; ++n)
; #pragma unroll
;                 for (int j = 0; j < 4; ++j) { cs[n][j] = 0.f; cq[n][j] = 0.f; }
; #pragma unroll
;             for (int ai = 0; ai < 2; ++ai)
; #pragma unroll
;                 for (int m = 0; m < 4; ++m) { bf16_t* rowp = Vt + ((size_t)(2 * u.pn + bj) * E + (row0 + ai * HALF + m * 16)) * 128 + wc * 32 + 8 * fq;
;                     f32x4 v0 = acc[ai][bj][m][0], v1 = acc[ai][bj][m][1];
; #pragma unroll
;                     for (int j = 0; j < 4; ++j) { v0[j] = fgelu(v0[j]); v1[j] = fgelu(v1[j]);
;                         cs[0][j] += v0[j]; cq[0][j] += v0[j] * v0[j]; cs[1][j] += v1[j]; cq[1][j] += v1[j] * v1[j]; }
;                     u32x4 w; w.x = cvt_pk_bf16(v0[0], v0[1]); w.y = cvt_pk_bf16(v0[2], v0[3]); w.z = cvt_pk_bf16(v1[0], v1[1]); w.w = cvt_pk_bf16(v1[2], v1[3]);
;                     *(u32x4*)rowp = w; }
	s_mov_b64 exec, -1
	s_nop 1
	v_mov_b32_e32 v172, 0
	v_mov_b32_e32 v173, 0
	v_mov_b32_e32 v174, 0
	v_mov_b32_e32 v175, 0
	v_mov_b32_e32 v176, 0
	v_mov_b32_e32 v177, 0
	v_mov_b32_e32 v178, 0
	v_mov_b32_e32 v179, 0
	v_mov_b32_e32 v180, 0
	v_mov_b32_e32 v181, 0
	v_mov_b32_e32 v182, 0
	v_mov_b32_e32 v183, 0
	v_mov_b32_e32 v184, 0
	v_mov_b32_e32 v185, 0
	v_mov_b32_e32 v186, 0
	v_mov_b32_e32 v187, 0
	v_mul_f32_e32 v188, v62, v62
	v_mul_f32_e32 v189, v63, v63
	v_mul_f32_e32 v190, v64, v64
	v_mul_f32_e32 v191, v65, v65
	v_mul_f32_e32 v192, v58, v58
	v_mul_f32_e32 v193, v59, v59
	v_mul_f32_e32 v194, v60, v60
	v_mul_f32_e32 v195, v61, v61
	v_fma_f32 v188, v188, s0, v223
	v_fma_f32 v189, v189, s0, v223
	v_fma_f32 v190, v190, s0, v223
	v_fma_f32 v191, v191, s0, v223
	v_fma_f32 v192, v192, s0, v223
	v_fma_f32 v193, v193, s0, v223
	v_fma_f32 v194, v194, s0, v223
	v_fma_f32 v195, v195, s0, v223
	v_mul_f32_e32 v188, v188, v62
	v_mul_f32_e32 v189, v189, v63
	v_mul_f32_e32 v190, v190, v64
	v_mul_f32_e32 v191, v191, v65
	v_mul_f32_e32 v192, v192, v58
	v_mul_f32_e32 v193, v193, v59
	v_mul_f32_e32 v194, v194, v60
	v_mul_f32_e32 v195, v195, v61
	v_exp_f32_e32 v188, v188
	v_exp_f32_e32 v189, v189
	v_exp_f32_e32 v190, v190
	v_exp_f32_e32 v191, v191
	v_exp_f32_e32 v192, v192
	v_exp_f32_e32 v193, v193
	v_exp_f32_e32 v194, v194
	v_exp_f32_e32 v195, v195
	v_add_f32_e32 v188, 1.0, v188
	v_add_f32_e32 v189, 1.0, v189
	v_add_f32_e32 v190, 1.0, v190
	v_add_f32_e32 v191, 1.0, v191
	v_add_f32_e32 v192, 1.0, v192
	v_add_f32_e32 v193, 1.0, v193
	v_add_f32_e32 v194, 1.0, v194
	v_add_f32_e32 v195, 1.0, v195
	v_rcp_f32_e32 v188, v188
	v_rcp_f32_e32 v189, v189
	v_rcp_f32_e32 v190, v190
	v_rcp_f32_e32 v191, v191
	v_rcp_f32_e32 v192, v192
	v_rcp_f32_e32 v193, v193
	v_rcp_f32_e32 v194, v194
	v_rcp_f32_e32 v195, v195
	v_mul_f32_e32 v196, v62, v188
	v_mul_f32_e32 v197, v63, v189
	v_mul_f32_e32 v198, v64, v190
	v_mul_f32_e32 v199, v65, v191
	v_mul_f32_e32 v200, v58, v192
	v_mul_f32_e32 v201, v59, v193
	v_mul_f32_e32 v202, v60, v194
	v_mul_f32_e32 v203, v61, v195
	v_add_f32_e32 v172, v172, v196
	v_add_f32_e32 v174, v174, v197
	v_add_f32_e32 v176, v176, v198
	v_add_f32_e32 v178, v178, v199
	v_add_f32_e32 v180, v180, v200
	v_add_f32_e32 v182, v182, v201
	v_add_f32_e32 v184, v184, v202
	v_add_f32_e32 v186, v186, v203
	v_fmac_f32_e32 v173, v196, v196
	v_fmac_f32_e32 v175, v197, v197
	v_fmac_f32_e32 v177, v198, v198
	v_fmac_f32_e32 v179, v199, v199
	v_fmac_f32_e32 v181, v200, v200
	v_fmac_f32_e32 v183, v201, v201
	v_fmac_f32_e32 v185, v202, v202
	v_fmac_f32_e32 v187, v203, v203
	v_cvt_pk_bf16_f32 v204, v196, v197
	v_cvt_pk_bf16_f32 v205, v198, v199
	v_cvt_pk_bf16_f32 v206, v200, v201
	v_cvt_pk_bf16_f32 v207, v202, v203
	global_store_dwordx4 v212, v[204:207], s[20:21]
	v_mul_f32_e32 v188, v54, v54
	v_mul_f32_e32 v189, v55, v55
	v_mul_f32_e32 v190, v56, v56
	v_mul_f32_e32 v191, v57, v57
	v_mul_f32_e32 v192, v50, v50
	v_mul_f32_e32 v193, v51, v51
	v_mul_f32_e32 v194, v52, v52
	v_mul_f32_e32 v195, v53, v53
	v_fma_f32 v188, v188, s0, v223
	v_fma_f32 v189, v189, s0, v223
	v_fma_f32 v190, v190, s0, v223
	v_fma_f32 v191, v191, s0, v223
	v_fma_f32 v192, v192, s0, v223
	v_fma_f32 v193, v193, s0, v223
	v_fma_f32 v194, v194, s0, v223
	v_fma_f32 v195, v195, s0, v223
	v_mul_f32_e32 v188, v188, v54
	v_mul_f32_e32 v189, v189, v55
	v_mul_f32_e32 v190, v190, v56
	v_mul_f32_e32 v191, v191, v57
	v_mul_f32_e32 v192, v192, v50
	v_mul_f32_e32 v193, v193, v51
	v_mul_f32_e32 v194, v194, v52
	v_mul_f32_e32 v195, v195, v53
	v_exp_f32_e32 v188, v188
	v_exp_f32_e32 v189, v189
	v_exp_f32_e32 v190, v190
	v_exp_f32_e32 v191, v191
	v_exp_f32_e32 v192, v192
	v_exp_f32_e32 v193, v193
	v_exp_f32_e32 v194, v194
	v_exp_f32_e32 v195, v195
	v_add_f32_e32 v188, 1.0, v188
	v_add_f32_e32 v189, 1.0, v189
	v_add_f32_e32 v190, 1.0, v190
	v_add_f32_e32 v191, 1.0, v191
	v_add_f32_e32 v192, 1.0, v192
	v_add_f32_e32 v193, 1.0, v193
	v_add_f32_e32 v194, 1.0, v194
	v_add_f32_e32 v195, 1.0, v195
	v_rcp_f32_e32 v188, v188
	v_rcp_f32_e32 v189, v189
	v_rcp_f32_e32 v190, v190
	v_rcp_f32_e32 v191, v191
	v_rcp_f32_e32 v192, v192
	v_rcp_f32_e32 v193, v193
	v_rcp_f32_e32 v194, v194
	v_rcp_f32_e32 v195, v195
	v_mul_f32_e32 v196, v54, v188
	v_mul_f32_e32 v197, v55, v189
	v_mul_f32_e32 v198, v56, v190
	v_mul_f32_e32 v199, v57, v191
	v_mul_f32_e32 v200, v50, v192
	v_mul_f32_e32 v201, v51, v193
	v_mul_f32_e32 v202, v52, v194
	v_mul_f32_e32 v203, v53, v195
	v_add_f32_e32 v172, v172, v196
	v_add_f32_e32 v174, v174, v197
	v_add_f32_e32 v176, v176, v198
	v_add_f32_e32 v178, v178, v199
	v_add_f32_e32 v180, v180, v200
	v_add_f32_e32 v182, v182, v201
	v_add_f32_e32 v184, v184, v202
	v_add_f32_e32 v186, v186, v203
	v_fmac_f32_e32 v173, v196, v196
	v_fmac_f32_e32 v175, v197, v197
	v_fmac_f32_e32 v177, v198, v198
	v_fmac_f32_e32 v179, v199, v199
	v_fmac_f32_e32 v181, v200, v200
	v_fmac_f32_e32 v183, v201, v201
	v_fmac_f32_e32 v185, v202, v202
	v_fmac_f32_e32 v187, v203, v203
	v_cvt_pk_bf16_f32 v208, v196, v197
	v_cvt_pk_bf16_f32 v209, v198, v199
	v_cvt_pk_bf16_f32 v210, v200, v201
	v_cvt_pk_bf16_f32 v211, v202, v203
	global_store_dwordx4 v213, v[208:211], s[20:21]
	v_mul_f32_e32 v188, v26, v26
	v_mul_f32_e32 v189, v27, v27
	v_mul_f32_e32 v190, v28, v28
	v_mul_f32_e32 v191, v29, v29
	v_mul_f32_e32 v192, v46, v46
	v_mul_f32_e32 v193, v47, v47
	v_mul_f32_e32 v194, v48, v48
	v_mul_f32_e32 v195, v49, v49
	v_fma_f32 v188, v188, s0, v223
	v_fma_f32 v189, v189, s0, v223
	v_fma_f32 v190, v190, s0, v223
	v_fma_f32 v191, v191, s0, v223
	v_fma_f32 v192, v192, s0, v223
	v_fma_f32 v193, v193, s0, v223
	v_fma_f32 v194, v194, s0, v223
	v_fma_f32 v195, v195, s0, v223
; __device__ __forceinline__ unsigned cvt_pk_bf16(float lo, float hi) { unsigned r; asm volatile("v_cvt_pk_bf16_f32 %0, %1, %2" : "=v"(r) : "v"(lo), "v"(hi)); return r; }
; __device__ __forceinline__ float fgelu(float x) { const float u = x * (1.0f + 0.044715f * x * x); return x * fsigmoid(1.59576912f * u); }
;     EPI_ZERO_INIT
;     __device__ __forceinline__ void operator()(AccRef acc, const Unit& u, int sw) const {
;     ...
;             for (int ai = 0; ai < 2; ++ai)
; #pragma unroll
;                 for (int m = 0; m < 4; ++m) { bf16_t* rowp = Vt + ((size_t)(2 * u.pn + bj) * E + (row0 + ai * HALF + m * 16)) * 128 + wc * 32 + 8 * fq;
;                     f32x4 v0 = acc[ai][bj][m][0], v1 = acc[ai][bj][m][1];
; #pragma unroll
;                     for (int j = 0; j < 4; ++j) { v0[j] = fgelu(v0[j]); v1[j] = fgelu(v1[j]);
;                         cs[0][j] += v0[j]; cq[0][j] += v0[j] * v0[j]; cs[1][j] += v1[j]; cq[1][j] += v1[j] * v1[j]; }
;                     u32x4 w; w.x = cvt_pk_bf16(v0[0], v0[1]); w.y = cvt_pk_bf16(v0[2], v0[3]); w.z = cvt_pk_bf16(v1[0], v1[1]); w.w = cvt_pk_bf16(v1[2], v1[3]);
;                     *(u32x4*)rowp = w; }
	v_mul_f32_e32 v188, v188, v26
	v_mul_f32_e32 v189, v189, v27
	v_mul_f32_e32 v190, v190, v28
	v_mul_f32_e32 v191, v191, v29
	v_mul_f32_e32 v192, v192, v46
	v_mul_f32_e32 v193, v193, v47
	v_mul_f32_e32 v194, v194, v48
	v_mul_f32_e32 v195, v195, v49
	v_exp_f32_e32 v188, v188
	v_exp_f32_e32 v189, v189
	v_exp_f32_e32 v190, v190
	v_exp_f32_e32 v191, v191
	v_exp_f32_e32 v192, v192
	v_exp_f32_e32 v193, v193
	v_exp_f32_e32 v194, v194
	v_exp_f32_e32 v195, v195
	v_add_f32_e32 v188, 1.0, v188
	v_add_f32_e32 v189, 1.0, v189
	v_add_f32_e32 v190, 1.0, v190
	v_add_f32_e32 v191, 1.0, v191
	v_add_f32_e32 v192, 1.0, v192
	v_add_f32_e32 v193, 1.0, v193
	v_add_f32_e32 v194, 1.0, v194
	v_add_f32_e32 v195, 1.0, v195
	v_rcp_f32_e32 v188, v188
	v_rcp_f32_e32 v189, v189
	v_rcp_f32_e32 v190, v190
	v_rcp_f32_e32 v191, v191
	v_rcp_f32_e32 v192, v192
	v_rcp_f32_e32 v193, v193
	v_rcp_f32_e32 v194, v194
	v_rcp_f32_e32 v195, v195
	v_mul_f32_e32 v196, v26, v188
	v_mul_f32_e32 v197, v27, v189
	v_mul_f32_e32 v198, v28, v190
	v_mul_f32_e32 v199, v29, v191
	v_mul_f32_e32 v200, v46, v192
	v_mul_f32_e32 v201, v47, v193
	v_mul_f32_e32 v202, v48, v194
	v_mul_f32_e32 v203, v49, v195
	v_add_f32_e32 v172, v172, v196
	v_add_f32_e32 v174, v174, v197
	v_add_f32_e32 v176, v176, v198
	v_add_f32_e32 v178, v178, v199
	v_add_f32_e32 v180, v180, v200
	v_add_f32_e32 v182, v182, v201
	v_add_f32_e32 v184, v184, v202
	v_add_f32_e32 v186, v186, v203
	v_fmac_f32_e32 v173, v196, v196
	v_fmac_f32_e32 v175, v197, v197
	v_fmac_f32_e32 v177, v198, v198
	v_fmac_f32_e32 v179, v199, v199
	v_fmac_f32_e32 v181, v200, v200
	v_fmac_f32_e32 v183, v201, v201
	v_fmac_f32_e32 v185, v202, v202
	v_fmac_f32_e32 v187, v203, v203
	v_cvt_pk_bf16_f32 v204, v196, v197
	v_cvt_pk_bf16_f32 v205, v198, v199
	v_cvt_pk_bf16_f32 v206, v200, v201
	v_cvt_pk_bf16_f32 v207, v202, v203
	global_store_dwordx4 v214, v[204:207], s[20:21]
	v_mul_f32_e32 v188, v22, v22
	v_mul_f32_e32 v189, v23, v23
	v_mul_f32_e32 v190, v24, v24
	v_mul_f32_e32 v191, v25, v25
	v_mul_f32_e32 v192, v42, v42
	v_mul_f32_e32 v193, v43, v43
	v_mul_f32_e32 v194, v44, v44
	v_mul_f32_e32 v195, v45, v45
	v_fma_f32 v188, v188, s0, v223
	v_fma_f32 v189, v189, s0, v223
	v_fma_f32 v190, v190, s0, v223
	v_fma_f32 v191, v191, s0, v223
	v_fma_f32 v192, v192, s0, v223
	v_fma_f32 v193, v193, s0, v223
	v_fma_f32 v194, v194, s0, v223
	v_fma_f32 v195, v195, s0, v223
	v_mul_f32_e32 v188, v188, v22
	v_mul_f32_e32 v189, v189, v23
	v_mul_f32_e32 v190, v190, v24
	v_mul_f32_e32 v191, v191, v25
	v_mul_f32_e32 v192, v192, v42
	v_mul_f32_e32 v193, v193, v43
	v_mul_f32_e32 v194, v194, v44
	v_mul_f32_e32 v195, v195, v45
	v_exp_f32_e32 v188, v188
	v_exp_f32_e32 v189, v189
	v_exp_f32_e32 v190, v190
	v_exp_f32_e32 v191, v191
	v_exp_f32_e32 v192, v192
	v_exp_f32_e32 v193, v193
	v_exp_f32_e32 v194, v194
	v_exp_f32_e32 v195, v195
	v_add_f32_e32 v188, 1.0, v188
	v_add_f32_e32 v189, 1.0, v189
	v_add_f32_e32 v190, 1.0, v190
	v_add_f32_e32 v191, 1.0, v191
	v_add_f32_e32 v192, 1.0, v192
	v_add_f32_e32 v193, 1.0, v193
	v_add_f32_e32 v194, 1.0, v194
	v_add_f32_e32 v195, 1.0, v195
	v_rcp_f32_e32 v188, v188
	v_rcp_f32_e32 v189, v189
	v_rcp_f32_e32 v190, v190
	v_rcp_f32_e32 v191, v191
	v_rcp_f32_e32 v192, v192
	v_rcp_f32_e32 v193, v193
	v_rcp_f32_e32 v194, v194
	v_rcp_f32_e32 v195, v195
	v_mul_f32_e32 v196, v22, v188
	v_mul_f32_e32 v197, v23, v189
	v_mul_f32_e32 v198, v24, v190
	v_mul_f32_e32 v199, v25, v191
	v_mul_f32_e32 v200, v42, v192
	v_mul_f32_e32 v201, v43, v193
	v_mul_f32_e32 v202, v44, v194
	v_mul_f32_e32 v203, v45, v195
	v_add_f32_e32 v172, v172, v196
	v_add_f32_e32 v174, v174, v197
	v_add_f32_e32 v176, v176, v198
	v_add_f32_e32 v178, v178, v199
	v_add_f32_e32 v180, v180, v200
	v_add_f32_e32 v182, v182, v201
	v_add_f32_e32 v184, v184, v202
	v_add_f32_e32 v186, v186, v203
	v_fmac_f32_e32 v173, v196, v196
	v_fmac_f32_e32 v175, v197, v197
	v_fmac_f32_e32 v177, v198, v198
	v_fmac_f32_e32 v179, v199, v199
	v_fmac_f32_e32 v181, v200, v200
	v_fmac_f32_e32 v183, v201, v201
	v_fmac_f32_e32 v185, v202, v202
	v_fmac_f32_e32 v187, v203, v203
	v_cvt_pk_bf16_f32 v208, v196, v197
	v_cvt_pk_bf16_f32 v209, v198, v199
	v_cvt_pk_bf16_f32 v210, v200, v201
	v_cvt_pk_bf16_f32 v211, v202, v203
	global_store_dwordx4 v215, v[208:211], s[20:21]
	v_mul_f32_e32 v188, v14, v14
	v_mul_f32_e32 v189, v15, v15
	v_mul_f32_e32 v190, v16, v16
	v_mul_f32_e32 v191, v17, v17
	v_mul_f32_e32 v192, v38, v38
	v_mul_f32_e32 v193, v39, v39
	v_mul_f32_e32 v194, v40, v40
	v_mul_f32_e32 v195, v41, v41
	v_fma_f32 v188, v188, s0, v223
	v_fma_f32 v189, v189, s0, v223
	v_fma_f32 v190, v190, s0, v223
	v_fma_f32 v191, v191, s0, v223
	v_fma_f32 v192, v192, s0, v223
	v_fma_f32 v193, v193, s0, v223
	v_fma_f32 v194, v194, s0, v223
	v_fma_f32 v195, v195, s0, v223
	v_mul_f32_e32 v188, v188, v14
	v_mul_f32_e32 v189, v189, v15
	v_mul_f32_e32 v190, v190, v16
	v_mul_f32_e32 v191, v191, v17
	v_mul_f32_e32 v192, v192, v38
	v_mul_f32_e32 v193, v193, v39
	v_mul_f32_e32 v194, v194, v40
	v_mul_f32_e32 v195, v195, v41
	v_exp_f32_e32 v188, v188
	v_exp_f32_e32 v189, v189
	v_exp_f32_e32 v190, v190
	v_exp_f32_e32 v191, v191
	v_exp_f32_e32 v192, v192
	v_exp_f32_e32 v193, v193
	v_exp_f32_e32 v194, v194
	v_exp_f32_e32 v195, v195
	v_add_f32_e32 v188, 1.0, v188
	v_add_f32_e32 v189, 1.0, v189
	v_add_f32_e32 v190, 1.0, v190
	v_add_f32_e32 v191, 1.0, v191
	v_add_f32_e32 v192, 1.0, v192
	v_add_f32_e32 v193, 1.0, v193
	v_add_f32_e32 v194, 1.0, v194
	v_add_f32_e32 v195, 1.0, v195
	v_rcp_f32_e32 v188, v188
	v_rcp_f32_e32 v189, v189
	v_rcp_f32_e32 v190, v190
	v_rcp_f32_e32 v191, v191
	v_rcp_f32_e32 v192, v192
	v_rcp_f32_e32 v193, v193
	v_rcp_f32_e32 v194, v194
	v_rcp_f32_e32 v195, v195
; __device__ __forceinline__ unsigned cvt_pk_bf16(float lo, float hi) { unsigned r; asm volatile("v_cvt_pk_bf16_f32 %0, %1, %2" : "=v"(r) : "v"(lo), "v"(hi)); return r; }
; __device__ __forceinline__ float fgelu(float x) { const float u = x * (1.0f + 0.044715f * x * x); return x * fsigmoid(1.59576912f * u); }
;     EPI_ZERO_INIT
;     __device__ __forceinline__ void operator()(AccRef acc, const Unit& u, int sw) const {
;     ...
;             for (int ai = 0; ai < 2; ++ai)
; #pragma unroll
;                 for (int m = 0; m < 4; ++m) { bf16_t* rowp = Vt + ((size_t)(2 * u.pn + bj) * E + (row0 + ai * HALF + m * 16)) * 128 + wc * 32 + 8 * fq;
;                     f32x4 v0 = acc[ai][bj][m][0], v1 = acc[ai][bj][m][1];
; #pragma unroll
;                     for (int j = 0; j < 4; ++j) { v0[j] = fgelu(v0[j]); v1[j] = fgelu(v1[j]);
;                         cs[0][j] += v0[j]; cq[0][j] += v0[j] * v0[j]; cs[1][j] += v1[j]; cq[1][j] += v1[j] * v1[j]; }
;                     u32x4 w; w.x = cvt_pk_bf16(v0[0], v0[1]); w.y = cvt_pk_bf16(v0[2], v0[3]); w.z = cvt_pk_bf16(v1[0], v1[1]); w.w = cvt_pk_bf16(v1[2], v1[3]);
;                     *(u32x4*)rowp = w; }
	v_mul_f32_e32 v196, v14, v188
	v_mul_f32_e32 v197, v15, v189
	v_mul_f32_e32 v198, v16, v190
	v_mul_f32_e32 v199, v17, v191
	v_mul_f32_e32 v200, v38, v192
	v_mul_f32_e32 v201, v39, v193
	v_mul_f32_e32 v202, v40, v194
	v_mul_f32_e32 v203, v41, v195
	v_add_f32_e32 v172, v172, v196
	v_add_f32_e32 v174, v174, v197
	v_add_f32_e32 v176, v176, v198
	v_add_f32_e32 v178, v178, v199
	v_add_f32_e32 v180, v180, v200
	v_add_f32_e32 v182, v182, v201
	v_add_f32_e32 v184, v184, v202
	v_add_f32_e32 v186, v186, v203
	v_fmac_f32_e32 v173, v196, v196
	v_fmac_f32_e32 v175, v197, v197
	v_fmac_f32_e32 v177, v198, v198
	v_fmac_f32_e32 v179, v199, v199
	v_fmac_f32_e32 v181, v200, v200
	v_fmac_f32_e32 v183, v201, v201
	v_fmac_f32_e32 v185, v202, v202
	v_fmac_f32_e32 v187, v203, v203
	v_cvt_pk_bf16_f32 v204, v196, v197
	v_cvt_pk_bf16_f32 v205, v198, v199
	v_cvt_pk_bf16_f32 v206, v200, v201
	v_cvt_pk_bf16_f32 v207, v202, v203
	global_store_dwordx4 v216, v[204:207], s[20:21]
	v_mul_f32_e32 v188, v10, v10
	v_mul_f32_e32 v189, v11, v11
	v_mul_f32_e32 v190, v12, v12
	v_mul_f32_e32 v191, v13, v13
	v_mul_f32_e32 v192, v34, v34
	v_mul_f32_e32 v193, v35, v35
	v_mul_f32_e32 v194, v36, v36
	v_mul_f32_e32 v195, v37, v37
	v_fma_f32 v188, v188, s0, v223
	v_fma_f32 v189, v189, s0, v223
	v_fma_f32 v190, v190, s0, v223
	v_fma_f32 v191, v191, s0, v223
	v_fma_f32 v192, v192, s0, v223
	v_fma_f32 v193, v193, s0, v223
	v_fma_f32 v194, v194, s0, v223
	v_fma_f32 v195, v195, s0, v223
	v_mul_f32_e32 v188, v188, v10
	v_mul_f32_e32 v189, v189, v11
	v_mul_f32_e32 v190, v190, v12
	v_mul_f32_e32 v191, v191, v13
	v_mul_f32_e32 v192, v192, v34
	v_mul_f32_e32 v193, v193, v35
	v_mul_f32_e32 v194, v194, v36
	v_mul_f32_e32 v195, v195, v37
	v_exp_f32_e32 v188, v188
	v_exp_f32_e32 v189, v189
	v_exp_f32_e32 v190, v190
	v_exp_f32_e32 v191, v191
	v_exp_f32_e32 v192, v192
	v_exp_f32_e32 v193, v193
	v_exp_f32_e32 v194, v194
	v_exp_f32_e32 v195, v195
	v_add_f32_e32 v188, 1.0, v188
	v_add_f32_e32 v189, 1.0, v189
	v_add_f32_e32 v190, 1.0, v190
	v_add_f32_e32 v191, 1.0, v191
	v_add_f32_e32 v192, 1.0, v192
	v_add_f32_e32 v193, 1.0, v193
	v_add_f32_e32 v194, 1.0, v194
	v_add_f32_e32 v195, 1.0, v195
	v_rcp_f32_e32 v188, v188
	v_rcp_f32_e32 v189, v189
	v_rcp_f32_e32 v190, v190
	v_rcp_f32_e32 v191, v191
	v_rcp_f32_e32 v192, v192
	v_rcp_f32_e32 v193, v193
	v_rcp_f32_e32 v194, v194
	v_rcp_f32_e32 v195, v195
	v_mul_f32_e32 v196, v10, v188
	v_mul_f32_e32 v197, v11, v189
	v_mul_f32_e32 v198, v12, v190
	v_mul_f32_e32 v199, v13, v191
	v_mul_f32_e32 v200, v34, v192
	v_mul_f32_e32 v201, v35, v193
	v_mul_f32_e32 v202, v36, v194
	v_mul_f32_e32 v203, v37, v195
	v_add_f32_e32 v172, v172, v196
	v_add_f32_e32 v174, v174, v197
	v_add_f32_e32 v176, v176, v198
	v_add_f32_e32 v178, v178, v199
	v_add_f32_e32 v180, v180, v200
	v_add_f32_e32 v182, v182, v201
	v_add_f32_e32 v184, v184, v202
	v_add_f32_e32 v186, v186, v203
	v_fmac_f32_e32 v173, v196, v196
	v_fmac_f32_e32 v175, v197, v197
	v_fmac_f32_e32 v177, v198, v198
	v_fmac_f32_e32 v179, v199, v199
	v_fmac_f32_e32 v181, v200, v200
	v_fmac_f32_e32 v183, v201, v201
	v_fmac_f32_e32 v185, v202, v202
	v_fmac_f32_e32 v187, v203, v203
	v_cvt_pk_bf16_f32 v208, v196, v197
	v_cvt_pk_bf16_f32 v209, v198, v199
	v_cvt_pk_bf16_f32 v210, v200, v201
	v_cvt_pk_bf16_f32 v211, v202, v203
	global_store_dwordx4 v217, v[208:211], s[20:21]
	v_mul_f32_e32 v188, v6, v6
	v_mul_f32_e32 v189, v7, v7
	v_mul_f32_e32 v190, v8, v8
	v_mul_f32_e32 v191, v9, v9
	v_mul_f32_e32 v192, v30, v30
	v_mul_f32_e32 v193, v31, v31
	v_mul_f32_e32 v194, v32, v32
	v_mul_f32_e32 v195, v33, v33
	v_fma_f32 v188, v188, s0, v223
	v_fma_f32 v189, v189, s0, v223
	v_fma_f32 v190, v190, s0, v223
	v_fma_f32 v191, v191, s0, v223
	v_fma_f32 v192, v192, s0, v223
	v_fma_f32 v193, v193, s0, v223
	v_fma_f32 v194, v194, s0, v223
	v_fma_f32 v195, v195, s0, v223
	v_mul_f32_e32 v188, v188, v6
	v_mul_f32_e32 v189, v189, v7
	v_mul_f32_e32 v190, v190, v8
	v_mul_f32_e32 v191, v191, v9
	v_mul_f32_e32 v192, v192, v30
	v_mul_f32_e32 v193, v193, v31
	v_mul_f32_e32 v194, v194, v32
	v_mul_f32_e32 v195, v195, v33
	v_exp_f32_e32 v188, v188
	v_exp_f32_e32 v189, v189
	v_exp_f32_e32 v190, v190
	v_exp_f32_e32 v191, v191
	v_exp_f32_e32 v192, v192
	v_exp_f32_e32 v193, v193
	v_exp_f32_e32 v194, v194
	v_exp_f32_e32 v195, v195
	v_add_f32_e32 v188, 1.0, v188
	v_add_f32_e32 v189, 1.0, v189
	v_add_f32_e32 v190, 1.0, v190
	v_add_f32_e32 v191, 1.0, v191
	v_add_f32_e32 v192, 1.0, v192
	v_add_f32_e32 v193, 1.0, v193
	v_add_f32_e32 v194, 1.0, v194
	v_add_f32_e32 v195, 1.0, v195
	v_rcp_f32_e32 v188, v188
	v_rcp_f32_e32 v189, v189
	v_rcp_f32_e32 v190, v190
	v_rcp_f32_e32 v191, v191
	v_rcp_f32_e32 v192, v192
	v_rcp_f32_e32 v193, v193
	v_rcp_f32_e32 v194, v194
	v_rcp_f32_e32 v195, v195
	v_mul_f32_e32 v196, v6, v188
	v_mul_f32_e32 v197, v7, v189
	v_mul_f32_e32 v198, v8, v190
	v_mul_f32_e32 v199, v9, v191
	v_mul_f32_e32 v200, v30, v192
	v_mul_f32_e32 v201, v31, v193
	v_mul_f32_e32 v202, v32, v194
	v_mul_f32_e32 v203, v33, v195
	v_add_f32_e32 v172, v172, v196
	v_add_f32_e32 v174, v174, v197
	v_add_f32_e32 v176, v176, v198
	v_add_f32_e32 v178, v178, v199
	v_add_f32_e32 v180, v180, v200
	v_add_f32_e32 v182, v182, v201
	v_add_f32_e32 v184, v184, v202
	v_add_f32_e32 v186, v186, v203
	v_fmac_f32_e32 v173, v196, v196
	v_fmac_f32_e32 v175, v197, v197
	v_fmac_f32_e32 v177, v198, v198
	v_fmac_f32_e32 v179, v199, v199
	v_fmac_f32_e32 v181, v200, v200
	v_fmac_f32_e32 v183, v201, v201
	v_fmac_f32_e32 v185, v202, v202
	v_fmac_f32_e32 v187, v203, v203
	v_cvt_pk_bf16_f32 v204, v196, v197
	v_cvt_pk_bf16_f32 v205, v198, v199
	v_cvt_pk_bf16_f32 v206, v200, v201
	v_cvt_pk_bf16_f32 v207, v202, v203
; __device__ __forceinline__ unsigned cvt_pk_bf16(float lo, float hi) { unsigned r; asm volatile("v_cvt_pk_bf16_f32 %0, %1, %2" : "=v"(r) : "v"(lo), "v"(hi)); return r; }
; __device__ __forceinline__ float fgelu(float x) { const float u = x * (1.0f + 0.044715f * x * x); return x * fsigmoid(1.59576912f * u); }
; template <int K> __device__ __forceinline__ float row_ror(float v) { return __int_as_float(__builtin_amdgcn_update_dpp(0, __float_as_int(v), 0x120 + K, 0xF, 0xF, false)); }
;     EPI_ZERO_INIT
;     __device__ __forceinline__ void operator()(AccRef acc, const Unit& u, int sw) const {
;     ...
;                 for (int m = 0; m < 4; ++m) { bf16_t* rowp = Vt + ((size_t)(2 * u.pn + bj) * E + (row0 + ai * HALF + m * 16)) * 128 + wc * 32 + 8 * fq;
;                     f32x4 v0 = acc[ai][bj][m][0], v1 = acc[ai][bj][m][1];
; #pragma unroll
;                     for (int j = 0; j < 4; ++j) { v0[j] = fgelu(v0[j]); v1[j] = fgelu(v1[j]);
;                         cs[0][j] += v0[j]; cq[0][j] += v0[j] * v0[j]; cs[1][j] += v1[j]; cq[1][j] += v1[j] * v1[j]; }
;                     u32x4 w; w.x = cvt_pk_bf16(v0[0], v0[1]); w.y = cvt_pk_bf16(v0[2], v0[3]); w.z = cvt_pk_bf16(v1[0], v1[1]); w.w = cvt_pk_bf16(v1[2], v1[3]);
;                     *(u32x4*)rowp = w; }
;             f32x2* sp = VSTAT + (size_t)(u.pm * 2 + wr) * M + col0 + bj * HALF;
; #pragma unroll
;             for (int n = 0; n < 2; ++n)
; #pragma unroll
;                 for (int j = 0; j < 4; ++j) { float s = cs[n][j], q = cq[n][j];
;                     s += row_ror<8>(s); q += row_ror<8>(q); s += row_ror<4>(s); q += row_ror<4>(q);
;                     s += row_ror<2>(s); q += row_ror<2>(q); s += row_ror<1>(s); q += row_ror<1>(q);
	global_store_dwordx4 v218, v[204:207], s[20:21]
	v_mul_f32_e32 v188, v2, v2
	v_mul_f32_e32 v189, v3, v3
	v_mul_f32_e32 v190, v4, v4
	v_mul_f32_e32 v191, v5, v5
	v_mul_f32_e32 v192, v18, v18
	v_mul_f32_e32 v193, v19, v19
	v_mul_f32_e32 v194, v20, v20
	v_mul_f32_e32 v195, v21, v21
	v_fma_f32 v188, v188, s0, v223
	v_fma_f32 v189, v189, s0, v223
	v_fma_f32 v190, v190, s0, v223
	v_fma_f32 v191, v191, s0, v223
	v_fma_f32 v192, v192, s0, v223
	v_fma_f32 v193, v193, s0, v223
	v_fma_f32 v194, v194, s0, v223
	v_fma_f32 v195, v195, s0, v223
	v_mul_f32_e32 v188, v188, v2
	v_mul_f32_e32 v189, v189, v3
	v_mul_f32_e32 v190, v190, v4
	v_mul_f32_e32 v191, v191, v5
	v_mul_f32_e32 v192, v192, v18
	v_mul_f32_e32 v193, v193, v19
	v_mul_f32_e32 v194, v194, v20
	v_mul_f32_e32 v195, v195, v21
	v_exp_f32_e32 v188, v188
	v_exp_f32_e32 v189, v189
	v_exp_f32_e32 v190, v190
	v_exp_f32_e32 v191, v191
	v_exp_f32_e32 v192, v192
	v_exp_f32_e32 v193, v193
	v_exp_f32_e32 v194, v194
	v_exp_f32_e32 v195, v195
	v_add_f32_e32 v188, 1.0, v188
	v_add_f32_e32 v189, 1.0, v189
	v_add_f32_e32 v190, 1.0, v190
	v_add_f32_e32 v191, 1.0, v191
	v_add_f32_e32 v192, 1.0, v192
	v_add_f32_e32 v193, 1.0, v193
	v_add_f32_e32 v194, 1.0, v194
	v_add_f32_e32 v195, 1.0, v195
	v_rcp_f32_e32 v188, v188
	v_rcp_f32_e32 v189, v189
	v_rcp_f32_e32 v190, v190
	v_rcp_f32_e32 v191, v191
	v_rcp_f32_e32 v192, v192
	v_rcp_f32_e32 v193, v193
	v_rcp_f32_e32 v194, v194
	v_rcp_f32_e32 v195, v195
	v_mul_f32_e32 v196, v2, v188
	v_mul_f32_e32 v197, v3, v189
	v_mul_f32_e32 v198, v4, v190
	v_mul_f32_e32 v199, v5, v191
	v_mul_f32_e32 v200, v18, v192
	v_mul_f32_e32 v201, v19, v193
	v_mul_f32_e32 v202, v20, v194
	v_mul_f32_e32 v203, v21, v195
	v_add_f32_e32 v172, v172, v196
	v_add_f32_e32 v174, v174, v197
	v_add_f32_e32 v176, v176, v198
	v_add_f32_e32 v178, v178, v199
	v_add_f32_e32 v180, v180, v200
	v_add_f32_e32 v182, v182, v201
	v_add_f32_e32 v184, v184, v202
	v_add_f32_e32 v186, v186, v203
	v_fmac_f32_e32 v173, v196, v196
	v_fmac_f32_e32 v175, v197, v197
	v_fmac_f32_e32 v177, v198, v198
	v_fmac_f32_e32 v179, v199, v199
	v_fmac_f32_e32 v181, v200, v200
	v_fmac_f32_e32 v183, v201, v201
	v_fmac_f32_e32 v185, v202, v202
	v_fmac_f32_e32 v187, v203, v203
	v_cvt_pk_bf16_f32 v208, v196, v197
	v_cvt_pk_bf16_f32 v209, v198, v199
	v_cvt_pk_bf16_f32 v210, v200, v201
	v_cvt_pk_bf16_f32 v211, v202, v203
	global_store_dwordx4 v219, v[208:211], s[20:21]
	v_add_f32_dpp v172, v172, v172 row_ror:8 row_mask:0xf bank_mask:0xf
	v_add_f32_dpp v173, v173, v173 row_ror:8 row_mask:0xf bank_mask:0xf
	v_add_f32_dpp v174, v174, v174 row_ror:8 row_mask:0xf bank_mask:0xf
	v_add_f32_dpp v175, v175, v175 row_ror:8 row_mask:0xf bank_mask:0xf
	v_add_f32_dpp v176, v176, v176 row_ror:8 row_mask:0xf bank_mask:0xf
	v_add_f32_dpp v177, v177, v177 row_ror:8 row_mask:0xf bank_mask:0xf
	v_add_f32_dpp v178, v178, v178 row_ror:8 row_mask:0xf bank_mask:0xf
	v_add_f32_dpp v179, v179, v179 row_ror:8 row_mask:0xf bank_mask:0xf
	v_add_f32_dpp v180, v180, v180 row_ror:8 row_mask:0xf bank_mask:0xf
	v_add_f32_dpp v181, v181, v181 row_ror:8 row_mask:0xf bank_mask:0xf
	v_add_f32_dpp v182, v182, v182 row_ror:8 row_mask:0xf bank_mask:0xf
	v_add_f32_dpp v183, v183, v183 row_ror:8 row_mask:0xf bank_mask:0xf
	v_add_f32_dpp v184, v184, v184 row_ror:8 row_mask:0xf bank_mask:0xf
	v_add_f32_dpp v185, v185, v185 row_ror:8 row_mask:0xf bank_mask:0xf
	v_add_f32_dpp v186, v186, v186 row_ror:8 row_mask:0xf bank_mask:0xf
	v_add_f32_dpp v187, v187, v187 row_ror:8 row_mask:0xf bank_mask:0xf
	v_add_f32_dpp v172, v172, v172 row_ror:4 row_mask:0xf bank_mask:0xf
; template <int K> __device__ __forceinline__ float row_ror(float v) { return __int_as_float(__builtin_amdgcn_update_dpp(0, __float_as_int(v), 0x120 + K, 0xF, 0xF, false)); }
;     EPI_ZERO_INIT
;     __device__ __forceinline__ void operator()(AccRef acc, const Unit& u, int sw) const {
;     ...
;                 for (int j = 0; j < 4; ++j) { float s = cs[n][j], q = cq[n][j];
;                     s += row_ror<8>(s); q += row_ror<8>(q); s += row_ror<4>(s); q += row_ror<4>(q);
;                     s += row_ror<2>(s); q += row_ror<2>(q); s += row_ror<1>(s); q += row_ror<1>(q);
;                     if (fr == 0) sp[4 * n + j] = (f32x2){s, q}; }
	v_add_f32_dpp v173, v173, v173 row_ror:4 row_mask:0xf bank_mask:0xf
	v_add_f32_dpp v174, v174, v174 row_ror:4 row_mask:0xf bank_mask:0xf
	v_add_f32_dpp v175, v175, v175 row_ror:4 row_mask:0xf bank_mask:0xf
	v_add_f32_dpp v176, v176, v176 row_ror:4 row_mask:0xf bank_mask:0xf
	v_add_f32_dpp v177, v177, v177 row_ror:4 row_mask:0xf bank_mask:0xf
	v_add_f32_dpp v178, v178, v178 row_ror:4 row_mask:0xf bank_mask:0xf
	v_add_f32_dpp v179, v179, v179 row_ror:4 row_mask:0xf bank_mask:0xf
	v_add_f32_dpp v180, v180, v180 row_ror:4 row_mask:0xf bank_mask:0xf
	v_add_f32_dpp v181, v181, v181 row_ror:4 row_mask:0xf bank_mask:0xf
	v_add_f32_dpp v182, v182, v182 row_ror:4 row_mask:0xf bank_mask:0xf
	v_add_f32_dpp v183, v183, v183 row_ror:4 row_mask:0xf bank_mask:0xf
	v_add_f32_dpp v184, v184, v184 row_ror:4 row_mask:0xf bank_mask:0xf
	v_add_f32_dpp v185, v185, v185 row_ror:4 row_mask:0xf bank_mask:0xf
	v_add_f32_dpp v186, v186, v186 row_ror:4 row_mask:0xf bank_mask:0xf
	v_add_f32_dpp v187, v187, v187 row_ror:4 row_mask:0xf bank_mask:0xf
	v_add_f32_dpp v172, v172, v172 row_ror:2 row_mask:0xf bank_mask:0xf
	v_add_f32_dpp v173, v173, v173 row_ror:2 row_mask:0xf bank_mask:0xf
	v_add_f32_dpp v174, v174, v174 row_ror:2 row_mask:0xf bank_mask:0xf
	v_add_f32_dpp v175, v175, v175 row_ror:2 row_mask:0xf bank_mask:0xf
	v_add_f32_dpp v176, v176, v176 row_ror:2 row_mask:0xf bank_mask:0xf
	v_add_f32_dpp v177, v177, v177 row_ror:2 row_mask:0xf bank_mask:0xf
	v_add_f32_dpp v178, v178, v178 row_ror:2 row_mask:0xf bank_mask:0xf
	v_add_f32_dpp v179, v179, v179 row_ror:2 row_mask:0xf bank_mask:0xf
	v_add_f32_dpp v180, v180, v180 row_ror:2 row_mask:0xf bank_mask:0xf
	v_add_f32_dpp v181, v181, v181 row_ror:2 row_mask:0xf bank_mask:0xf
	v_add_f32_dpp v182, v182, v182 row_ror:2 row_mask:0xf bank_mask:0xf
	v_add_f32_dpp v183, v183, v183 row_ror:2 row_mask:0xf bank_mask:0xf
	v_add_f32_dpp v184, v184, v184 row_ror:2 row_mask:0xf bank_mask:0xf
	v_add_f32_dpp v185, v185, v185 row_ror:2 row_mask:0xf bank_mask:0xf
	v_add_f32_dpp v186, v186, v186 row_ror:2 row_mask:0xf bank_mask:0xf
	v_add_f32_dpp v187, v187, v187 row_ror:2 row_mask:0xf bank_mask:0xf
	v_add_f32_dpp v172, v172, v172 row_ror:1 row_mask:0xf bank_mask:0xf
	v_add_f32_dpp v173, v173, v173 row_ror:1 row_mask:0xf bank_mask:0xf
	v_add_f32_dpp v174, v174, v174 row_ror:1 row_mask:0xf bank_mask:0xf
	v_add_f32_dpp v175, v175, v175 row_ror:1 row_mask:0xf bank_mask:0xf
	v_add_f32_dpp v176, v176, v176 row_ror:1 row_mask:0xf bank_mask:0xf
	v_add_f32_dpp v177, v177, v177 row_ror:1 row_mask:0xf bank_mask:0xf
	v_add_f32_dpp v178, v178, v178 row_ror:1 row_mask:0xf bank_mask:0xf
	v_add_f32_dpp v179, v179, v179 row_ror:1 row_mask:0xf bank_mask:0xf
	v_add_f32_dpp v180, v180, v180 row_ror:1 row_mask:0xf bank_mask:0xf
	v_add_f32_dpp v181, v181, v181 row_ror:1 row_mask:0xf bank_mask:0xf
	v_add_f32_dpp v182, v182, v182 row_ror:1 row_mask:0xf bank_mask:0xf
	v_add_f32_dpp v183, v183, v183 row_ror:1 row_mask:0xf bank_mask:0xf
	v_add_f32_dpp v184, v184, v184 row_ror:1 row_mask:0xf bank_mask:0xf
	v_add_f32_dpp v185, v185, v185 row_ror:1 row_mask:0xf bank_mask:0xf
	v_add_f32_dpp v186, v186, v186 row_ror:1 row_mask:0xf bank_mask:0xf
	v_add_f32_dpp v187, v187, v187 row_ror:1 row_mask:0xf bank_mask:0xf
	s_nop 1
	s_mov_b64 exec, vcc
	global_store_dwordx4 v222, v[172:175], s[16:17] offset:1024
	global_store_dwordx4 v222, v[176:179], s[16:17] offset:1040
	global_store_dwordx4 v222, v[180:183], s[16:17] offset:1056
	global_store_dwordx4 v222, v[184:187], s[16:17] offset:1072
	s_mov_b64 exec, -1
	s_nop 1
	s_branch .LBB0_767

; __device__ __forceinline__ unsigned xb_add(unsigned* p, unsigned v) { return __hip_atomic_fetch_add(p, v, __ATOMIC_RELAXED, __HIP_MEMORY_SCOPE_AGENT); }
; __device__ __forceinline__ void xcd_barrier(const XcdBarrier& b, int local) {
;     ...
;         const unsigned old = xb_add(&bar[XB_XSUB(b.x)], 1u);
;         const unsigned gen = old / nloc;
;         if (old + 1u == (gen + 1u) * nloc) {
;             if (!local) {
;             __builtin_amdgcn_fence(__ATOMIC_RELEASE, "agent");
;             asm volatile("s_waitcnt vmcnt(0)" ::: "memory");
;             const unsigned og = xb_add(&bar[XB_TOP], 1u);
;             const unsigned tg = og / nx;
;             if (og + 1u == (tg + 1u) * nx) xb_add(&bar[XB_TOPGEN], 1u);
.LBB0_1393:
	s_mov_b64 s[6:7], exec
	v_mov_b32_e32 v2, 0x20000
	ds_read_b32 v2, v2 offset:48
	s_waitcnt lgkmcnt(0)
	v_readfirstlane_b32 s100, v2
	s_nop 3
	s_cmp_lg_u32 s100, 0
	s_cbranch_scc1 .Lwt_skipwb
	buffer_wbl2 sc1
.Lwt_skipwb:
	s_waitcnt lgkmcnt(0)
	s_waitcnt vmcnt(0)
	v_mbcnt_lo_u32_b32 v2, s6, 0
	v_mbcnt_hi_u32_b32 v2, s7, v2
	v_cmp_eq_u32_e32 vcc, 0, v2
	s_and_saveexec_b64 s[8:9], vcc
	s_cbranch_execz .LBB0_1395
	s_bcnt1_i32_b64 s6, s[6:7]
	v_mov_b32_e32 v3, s6
	v_mov_b32_e32 v4, 0x3000
	global_atomic_add v3, v4, v3, s[4:5] offset:1024 sc0
